# PRE phase: team 0 sleeps 256 cycles after every stage barrier (stagger between the two wave teams of each SIMD, all 12 later stages)
# baseline (speedup 1.0000x reference)
.LBB0_83:
	s_or_b64 exec, exec, s[30:31]
	v_mov_b32_e32 v1, v180
	s_waitcnt lgkmcnt(0)
	s_barrier
	s_bitcmp1_b32 s60, 0
	s_cbranch_scc1 .Lstg_1
	s_sleep 4
.Lstg_1:
	v_readlane_b32 s27, v253, 61
	v_and_b32_e32 v2, 31, v1
	v_or_b32_e32 v156, s43, v2
	v_bitop3_b32 v2, v2, 63, s43 bitop3:0x36
	v_ashrrev_i32_e32 v1, 5, v1
	v_cndmask_b32_e64 v2, v2, v156, s[36:37]
	v_mul_u32_u24_e32 v2, 0x90, v2
	s_waitcnt lgkmcnt(0)
	v_lshlrev_b32_e32 v3, 4, v1
	v_readlane_b32 s30, v253, 62
	v_add3_u32 v32, s27, v2, v3
	ds_read_b128 v[28:31], v32
	ds_read_b128 v[84:87], v32 offset:32
	ds_read_b128 v[88:91], v32 offset:64
	ds_read_b128 v[92:95], v32 offset:96
	v_add3_u32 v2, s30, v2, v3
	ds_read_b128 v[32:35], v2
	ds_read_b128 v[96:99], v2 offset:32
	ds_read_b128 v[148:151], v2 offset:64
	ds_read_b128 v[152:155], v2 offset:96
	s_waitcnt vmcnt(7) lgkmcnt(7)
	v_mfma_f32_32x32x16_bf16 v[36:51], v[20:23], v[28:31], 0
	v_add_u32_e32 v2, s47, v3
	v_add_u32_e32 v3, s46, v3
	v_lshlrev_b32_e32 v1, 3, v1
	s_waitcnt vmcnt(6) lgkmcnt(3)
	v_mfma_f32_32x32x16_bf16 v[20:35], v[24:27], v[32:35], 0
	s_waitcnt vmcnt(5)
	v_mfma_f32_32x32x16_bf16 v[36:51], v[60:63], v[84:87], v[36:51]
	ds_read_b128 v[60:63], v2 offset:32
	s_waitcnt vmcnt(4) lgkmcnt(3)
	v_mfma_f32_32x32x16_bf16 v[20:35], v[56:59], v[96:99], v[20:35]
	ds_read_b128 v[56:59], v2
	v_mov_b32_e32 v98, s30
	v_mov_b32_e32 v99, s27
	s_waitcnt vmcnt(3)
	v_mfma_f32_32x32x16_bf16 v[36:51], v[72:75], v[88:91], v[36:51]
	v_mov_b32_e32 v90, s76
	v_mad_u32_u24 v90, v156, s64, v90
	v_add3_u32 v1, v90, v1, s28
	s_waitcnt vmcnt(2) lgkmcnt(3)
	v_mfma_f32_32x32x16_bf16 v[20:35], v[64:67], v[148:151], v[20:35]
	s_waitcnt vmcnt(1)
	v_mfma_f32_32x32x16_bf16 v[36:51], v[68:71], v[92:95], v[36:51]
	ds_read_b128 v[64:67], v3
	ds_read_b128 v[68:71], v3 offset:32
	s_waitcnt vmcnt(0) lgkmcnt(4)
	v_mfma_f32_32x32x16_bf16 v[20:35], v[52:55], v[152:155], v[20:35]
	s_waitcnt lgkmcnt(2)
	s_nop 6
	v_add_f32_e32 v36, v36, v56
	v_mul_f32_e32 v36, 0xbfb8aa3b, v36
	v_exp_f32_e32 v36, v36
	s_nop 0
	v_add_f32_e32 v36, 1.0, v36
	s_waitcnt lgkmcnt(1)
	v_add_f32_e32 v20, v20, v64
	v_mul_f32_e32 v20, 0xbfb8aa3b, v20
	v_rcp_f32_e32 v74, v36
	v_add_f32_e32 v36, v37, v57
	v_exp_f32_e32 v20, v20
	v_mul_f32_e32 v36, 0xbfb8aa3b, v36
	v_add_f32_e32 v21, v21, v65
	v_exp_f32_e32 v36, v36
	v_mul_f32_e32 v21, 0xbfb8aa3b, v21
	v_exp_f32_e32 v21, v21
	v_add_f32_e32 v20, 1.0, v20
	v_rcp_f32_e32 v52, v20
	v_add_f32_e32 v20, 1.0, v36
	v_rcp_f32_e32 v75, v20
	v_add_f32_e32 v20, 1.0, v21
	v_add_f32_e32 v21, v38, v58
	v_mul_f32_e32 v21, 0xbfb8aa3b, v21
	v_add_f32_e32 v22, v22, v66
	v_exp_f32_e32 v21, v21
	v_mul_f32_e32 v22, 0xbfb8aa3b, v22
	v_exp_f32_e32 v22, v22
	v_rcp_f32_e32 v53, v20
	v_add_f32_e32 v20, 1.0, v21
	v_add_f32_e32 v21, v39, v59
	v_rcp_f32_e32 v84, v20
	v_add_f32_e32 v20, 1.0, v22
	v_mul_f32_e32 v21, 0xbfb8aa3b, v21
	v_add_f32_e32 v22, v23, v67
	v_exp_f32_e32 v21, v21
	v_mul_f32_e32 v22, 0xbfb8aa3b, v22
	v_exp_f32_e32 v22, v22
	v_rcp_f32_e32 v54, v20
	v_add_f32_e32 v20, 1.0, v21
	v_add_f32_e32 v21, v40, v60
	v_rcp_f32_e32 v85, v20
	v_add_f32_e32 v20, 1.0, v22
	v_mul_f32_e32 v21, 0xbfb8aa3b, v21
	s_waitcnt lgkmcnt(0)
	v_add_f32_e32 v22, v24, v68
	v_exp_f32_e32 v21, v21
	v_mul_f32_e32 v22, 0xbfb8aa3b, v22
	v_exp_f32_e32 v22, v22
	v_rcp_f32_e32 v55, v20
	v_add_f32_e32 v20, 1.0, v21
	v_add_f32_e32 v21, v41, v61
	v_rcp_f32_e32 v60, v20
	v_add_f32_e32 v20, 1.0, v22
	v_mul_f32_e32 v21, 0xbfb8aa3b, v21
	v_add_f32_e32 v22, v25, v69
	v_exp_f32_e32 v21, v21
	v_mul_f32_e32 v22, 0xbfb8aa3b, v22
	v_exp_f32_e32 v22, v22
	v_rcp_f32_e32 v56, v20
	v_add_f32_e32 v20, 1.0, v21
	v_add_f32_e32 v21, v42, v62
	v_rcp_f32_e32 v61, v20
	v_add_f32_e32 v20, 1.0, v22
	v_mul_f32_e32 v21, 0xbfb8aa3b, v21
	v_add_f32_e32 v22, v26, v70
	v_exp_f32_e32 v21, v21
	v_mul_f32_e32 v22, 0xbfb8aa3b, v22
	v_exp_f32_e32 v22, v22
	v_rcp_f32_e32 v57, v20
	v_add_f32_e32 v20, 1.0, v21
	v_rcp_f32_e32 v62, v20
	v_add_f32_e32 v20, 1.0, v22
	v_rcp_f32_e32 v58, v20
	v_add_f32_e32 v20, v43, v63
	v_mul_f32_e32 v20, 0xbfb8aa3b, v20
	v_exp_f32_e32 v20, v20
	v_add_f32_e32 v21, v27, v71
	v_mul_f32_e32 v21, 0xbfb8aa3b, v21
	v_exp_f32_e32 v24, v21
	v_add_f32_e32 v25, 1.0, v20
	ds_read_b128 v[20:23], v2 offset:64
	v_rcp_f32_e32 v63, v25
	v_add_f32_e32 v59, 1.0, v24
	ds_read_b128 v[24:27], v3 offset:64
	ds_read_b128 v[36:39], v2 offset:96
	ds_read_b128 v[40:43], v3 offset:96
	s_waitcnt lgkmcnt(3)
	v_add_f32_e32 v2, v44, v20
	v_mul_f32_e32 v2, 0xbfb8aa3b, v2
	s_waitcnt lgkmcnt(2)
	v_add_f32_e32 v3, v28, v24
	v_exp_f32_e32 v2, v2
	v_mul_f32_e32 v3, 0xbfb8aa3b, v3
	v_exp_f32_e32 v3, v3
	s_waitcnt lgkmcnt(1)
	v_add_f32_e32 v28, v51, v39
	v_add_f32_e32 v2, 1.0, v2
	v_rcp_f32_e32 v20, v2
	v_add_f32_e32 v2, 1.0, v3
	v_add_f32_e32 v3, v45, v21
	v_mul_f32_e32 v3, 0xbfb8aa3b, v3
	v_exp_f32_e32 v3, v3
	v_add_f32_e32 v21, v29, v25
	v_mul_f32_e32 v21, 0xbfb8aa3b, v21
	v_rcp_f32_e32 v64, v2
	v_add_f32_e32 v2, 1.0, v3
	v_add_f32_e32 v3, v46, v22
	v_exp_f32_e32 v24, v21
	v_mul_f32_e32 v3, 0xbfb8aa3b, v3
	v_exp_f32_e32 v3, v3
	v_add_f32_e32 v22, v30, v26
	v_mul_f32_e32 v22, 0xbfb8aa3b, v22
	v_rcp_f32_e32 v21, v2
	v_add_f32_e32 v2, 1.0, v24
	v_exp_f32_e32 v24, v22
	v_rcp_f32_e32 v65, v2
	v_add_f32_e32 v2, 1.0, v3
	v_add_f32_e32 v3, v47, v23
	v_mul_f32_e32 v3, 0xbfb8aa3b, v3
	v_add_f32_e32 v23, v31, v27
	v_exp_f32_e32 v3, v3
	v_mul_f32_e32 v23, 0xbfb8aa3b, v23
	v_rcp_f32_e32 v22, v2
	v_add_f32_e32 v2, 1.0, v24
	v_exp_f32_e32 v24, v23
	v_rcp_f32_e32 v66, v2
	v_add_f32_e32 v2, 1.0, v3
	v_add_f32_e32 v3, v48, v36
	v_rcp_f32_e32 v23, v2
	v_add_f32_e32 v2, 1.0, v24
	v_mul_f32_e32 v3, 0xbfb8aa3b, v3
	s_waitcnt lgkmcnt(0)
	v_add_f32_e32 v24, v32, v40
	v_exp_f32_e32 v3, v3
	v_mul_f32_e32 v24, 0xbfb8aa3b, v24
	v_exp_f32_e32 v25, v24
	v_rcp_f32_e32 v67, v2
	v_add_f32_e32 v2, 1.0, v3
	v_add_f32_e32 v3, v49, v37
	v_rcp_f32_e32 v24, v2
	v_add_f32_e32 v2, 1.0, v25
	v_mul_f32_e32 v3, 0xbfb8aa3b, v3
	v_add_f32_e32 v25, v33, v41
	v_exp_f32_e32 v3, v3
	v_mul_f32_e32 v25, 0xbfb8aa3b, v25
	v_exp_f32_e32 v26, v25
	v_add_f32_e32 v27, v34, v42
	v_add_f32_e32 v3, 1.0, v3
	v_mul_f32_e32 v27, 0xbfb8aa3b, v27
	v_add_f32_e32 v29, v35, v43
	v_rcp_f32_e32 v25, v3
	v_add_f32_e32 v3, 1.0, v26
	v_add_f32_e32 v26, v50, v38
	v_exp_f32_e32 v27, v27
	v_mul_f32_e32 v28, 0xbfb8aa3b, v28
	v_mul_f32_e32 v29, 0xbfb8aa3b, v29
	v_mul_f32_e32 v26, 0xbfb8aa3b, v26
	v_exp_f32_e32 v28, v28
	v_exp_f32_e32 v29, v29
	v_exp_f32_e32 v26, v26
	v_add_f32_e32 v27, 1.0, v27
	v_pk_mul_f32 v[44:45], v[74:75], s[86:87] op_sel_hi:[1,0]
	v_pk_mul_f32 v[46:47], v[84:85], s[86:87] op_sel_hi:[1,0]
	v_rcp_f32_e32 v72, v27
	v_add_f32_e32 v27, 1.0, v28
	v_add_f32_e32 v73, 1.0, v29
	v_cvt_pk_bf16_f32 v28, v44, 0
	v_cvt_pk_bf16_f32 v29, v45, 0
	v_cvt_pk_bf16_f32 v32, v46, 0
	v_cvt_pk_bf16_f32 v33, v47, 0
	v_add_f32_e32 v26, 1.0, v26
	v_lshlrev_b32_e32 v29, 16, v29
	v_lshlrev_b32_e32 v28, 16, v28
	v_lshlrev_b32_e32 v33, 16, v33
	v_lshlrev_b32_e32 v32, 16, v32
	v_rcp_f32_e32 v26, v26
	v_rcp_f32_e32 v27, v27
	v_pk_fma_f32 v[30:31], v[74:75], s[86:87], v[28:29] op_sel_hi:[1,0,1] neg_lo:[0,0,1] neg_hi:[0,0,1]
	v_pk_fma_f32 v[34:35], v[84:85], s[86:87], v[32:33] op_sel_hi:[1,0,1] neg_lo:[0,0,1] neg_hi:[0,0,1]
	v_pk_mul_f32 v[74:75], v[60:61], s[86:87] op_sel_hi:[1,0]
	v_pk_mul_f32 v[84:85], v[62:63], s[86:87] op_sel_hi:[1,0]
	v_cvt_pk_bf16_f32 v36, v74, 0
	v_cvt_pk_bf16_f32 v37, v75, 0
	v_cvt_pk_bf16_f32 v40, v84, 0
	v_cvt_pk_bf16_f32 v41, v85, 0
	v_lshlrev_b32_e32 v37, 16, v37
	v_lshlrev_b32_e32 v36, 16, v36
	v_lshlrev_b32_e32 v41, 16, v41
	v_lshlrev_b32_e32 v40, 16, v40
	v_pk_mul_f32 v[68:69], v[24:25], s[86:87] op_sel_hi:[1,0]
	v_pk_fma_f32 v[38:39], v[60:61], s[86:87], v[36:37] op_sel_hi:[1,0,1] neg_lo:[0,0,1] neg_hi:[0,0,1]
	v_pk_fma_f32 v[42:43], v[62:63], s[86:87], v[40:41] op_sel_hi:[1,0,1] neg_lo:[0,0,1] neg_hi:[0,0,1]
	v_pk_mul_f32 v[60:61], v[20:21], s[86:87] op_sel_hi:[1,0]
	v_pk_mul_f32 v[62:63], v[22:23], s[86:87] op_sel_hi:[1,0]
	v_cvt_pk_bf16_f32 v70, v68, 0
	v_cvt_pk_bf16_f32 v71, v69, 0
	v_cvt_pk_bf16_f32 v48, v60, 0
	v_cvt_pk_bf16_f32 v49, v61, 0
	v_cvt_pk_bf16_f32 v50, v62, 0
	v_cvt_pk_bf16_f32 v51, v63, 0
	v_lshlrev_b32_e32 v87, 16, v71
	v_lshlrev_b32_e32 v86, 16, v70
	v_pk_mul_f32 v[70:71], v[26:27], s[86:87] op_sel_hi:[1,0]
	v_lshlrev_b32_e32 v49, 16, v49
	v_lshlrev_b32_e32 v48, 16, v48
	v_lshlrev_b32_e32 v51, 16, v51
	v_lshlrev_b32_e32 v50, 16, v50
	v_cvt_pk_bf16_f32 v88, v70, 0
	v_cvt_pk_bf16_f32 v89, v71, 0
	v_pk_fma_f32 v[20:21], v[20:21], s[86:87], v[48:49] op_sel_hi:[1,0,1] neg_lo:[0,0,1] neg_hi:[0,0,1]
	v_pk_fma_f32 v[22:23], v[22:23], s[86:87], v[50:51] op_sel_hi:[1,0,1] neg_lo:[0,0,1] neg_hi:[0,0,1]
	v_pk_fma_f32 v[24:25], v[24:25], s[86:87], v[86:87] op_sel_hi:[1,0,1] neg_lo:[0,0,1] neg_hi:[0,0,1]
	v_lshlrev_b32_e32 v89, 16, v89
	v_lshlrev_b32_e32 v88, 16, v88
	v_cvt_pk_bf16_f32 v28, v28, v29
	v_cvt_pk_bf16_f32 v29, v32, v33
	v_cvt_pk_bf16_f32 v32, v36, v37
	v_cvt_pk_bf16_f32 v33, v40, v41
	v_add_u32_e32 v36, 0x9000, v1
	ds_write2_b64 v36, v[28:29], v[32:33] offset1:2
	v_cvt_pk_bf16_f32 v28, v48, v49
	v_cvt_pk_bf16_f32 v29, v50, v51
	v_cvt_pk_bf16_f32 v32, v86, v87
	v_cvt_pk_bf16_f32 v33, v88, v89
	v_cvt_pk_bf16_f32 v20, v20, v21
	v_cvt_pk_bf16_f32 v21, v22, v23
	v_cvt_pk_bf16_f32 v22, v24, v25
	v_pk_fma_f32 v[24:25], v[26:27], s[86:87], v[88:89] op_sel_hi:[1,0,1] neg_lo:[0,0,1] neg_hi:[0,0,1]
	ds_write2_b64 v36, v[28:29], v[32:33] offset0:4 offset1:6
	v_cvt_pk_bf16_f32 v28, v30, v31
	v_cvt_pk_bf16_f32 v29, v34, v35
	v_cvt_pk_bf16_f32 v30, v38, v39
	v_cvt_pk_bf16_f32 v31, v42, v43
	v_add_u32_e32 v1, 0xb000, v1
	v_cvt_pk_bf16_f32 v23, v24, v25
	ds_write2_b64 v1, v[28:29], v[30:31] offset0:128 offset1:130
	ds_write2_b64 v1, v[20:21], v[22:23] offset0:132 offset1:134
	v_mov_b32_e32 v1, v180
	s_waitcnt lgkmcnt(0)
	s_barrier
	s_bitcmp1_b32 s60, 0
	s_cbranch_scc1 .Lstg_2
	s_sleep 4
.Lstg_2:
	v_rcp_f32_e32 v59, v59
	v_add_u32_e32 v20, s42, v1
	v_ashrrev_i32_e32 v20, 3, v20
	v_cmp_gt_i32_e32 vcc, 32, v20
	v_lshlrev_b32_e32 v20, 8, v20
	v_lshlrev_b32_e32 v1, 5, v1
	v_cndmask_b32_e32 v21, v98, v99, vcc
	v_and_b32_e32 v20, 0x1f00, v20
	v_and_b32_e32 v1, 0xe0, v1
	v_add3_u32 v1, v21, v20, v1
	ds_write_b128 v1, v[76:79]
	ds_write_b128 v1, v[80:83] offset:16
	v_mov_b32_e32 v1, v180
	v_rcp_f32_e32 v2, v2
	v_ashrrev_i32_e32 v24, 2, v1
	v_lshlrev_b32_e32 v22, 2, v1
	v_and_b32_e32 v20, 16, v1
	v_and_b32_e32 v148, -8, v24
	v_lshrrev_b32_e32 v21, 2, v1
	v_and_b32_e32 v22, 12, v22
	v_and_or_b32 v21, v21, 3, v148
	v_or3_b32 v20, v20, v22, s91
	v_lshlrev_b32_e32 v20, 1, v20
	v_mul_lo_u32 v21, v21, s64
	v_add3_u32 v25, s76, v20, v21
	ds_read_b64_tr_b16 v[20:21], v25 offset:36864
	ds_read_b64_tr_b16 v[22:23], v25 offset:37440
	ds_read_b64_tr_b16 v[36:37], v25 offset:39168
	ds_read_b64_tr_b16 v[38:39], v25 offset:39744
	ds_read_b64_tr_b16 v[40:41], v25 offset:41472
	ds_read_b64_tr_b16 v[42:43], v25 offset:42048
	ds_read_b64_tr_b16 v[48:49], v25 offset:43776
	ds_read_b64_tr_b16 v[50:51], v25 offset:44352
	ds_read_b64_tr_b16 v[76:77], v25 offset:46080
	ds_read_b64_tr_b16 v[78:79], v25 offset:46656
	ds_read_b64_tr_b16 v[80:81], v25 offset:48384
	ds_read_b64_tr_b16 v[82:83], v25 offset:48960
	ds_read_b64_tr_b16 v[86:87], v25 offset:50688
	ds_read_b64_tr_b16 v[88:89], v25 offset:51264
	ds_read_b64_tr_b16 v[90:91], v25 offset:52992
	ds_read_b64_tr_b16 v[92:93], v25 offset:53568
	v_and_or_b32 v1, v1, 31, s43
	v_rcp_f32_e32 v3, v3
	v_rcp_f32_e32 v73, v73
	v_cmp_gt_i32_e32 vcc, v148, v1
	v_or_b32_e32 v24, 7, v24
	s_waitcnt lgkmcnt(0)
	s_barrier
	s_bitcmp1_b32 s60, 0
	s_cbranch_scc1 .Lstg_3
	s_sleep 4
.Lstg_3:
	v_cndmask_b32_e64 v25, v224, 0, vcc
	v_cmp_lt_i32_e32 vcc, v148, v1
	s_add_i32 s27, 0, 0xd800
	s_add_i32 s30, 0, 0x1d400
	v_cndmask_b32_e32 v26, 0, v224, vcc
	v_perm_b32 v94, v26, v25, s65
	v_or_b32_e32 v26, 2, v148
	v_or_b32_e32 v25, 3, v148
	v_cmp_gt_i32_e32 vcc, v26, v1
	s_nop 1
	v_cndmask_b32_e64 v26, v224, 0, vcc
	v_cmp_gt_i32_e32 vcc, v25, v1
	s_nop 1
	v_cndmask_b32_e64 v25, v224, 0, vcc
	v_perm_b32 v95, v25, v26, s65
	v_or_b32_e32 v26, 4, v148
	v_or_b32_e32 v25, 5, v148
	v_cmp_gt_i32_e32 vcc, v26, v1
	s_nop 1
	v_cndmask_b32_e64 v26, v224, 0, vcc
	v_cmp_gt_i32_e32 vcc, v25, v1
	s_nop 1
	v_cndmask_b32_e64 v25, v224, 0, vcc
	v_perm_b32 v96, v25, v26, s65
	v_or_b32_e32 v25, 6, v148
	v_cmp_gt_i32_e32 vcc, v25, v1
	s_nop 1
	v_cndmask_b32_e64 v25, v224, 0, vcc
	v_cmp_gt_i32_e32 vcc, v24, v1
	s_nop 1
	v_cndmask_b32_e64 v24, v224, 0, vcc
	v_perm_b32 v97, v24, v25, s65
	s_waitcnt lgkmcnt(14)
	s_nop 0
	v_mfma_f32_32x32x16_bf16 v[20:35], v[20:23], v[94:97], 0
	s_waitcnt lgkmcnt(6)
	v_mfma_f32_32x32x16_bf16 v[20:35], v[76:79], v[94:97], v[20:35]
	v_add_u32_e32 v76, 16, v148
	v_cmp_gt_i32_e32 vcc, v76, v1
	v_add_u32_e32 v77, 17, v148
	v_add_u32_e32 v78, 18, v148
	v_cndmask_b32_e64 v76, v224, 0, vcc
	v_cmp_gt_i32_e32 vcc, v77, v1
	v_add_u32_e32 v79, 20, v148
	v_add_u32_e32 v96, 22, v148
	v_cndmask_b32_e64 v94, v224, 0, vcc
	v_cmp_gt_i32_e32 vcc, v78, v1
	v_add_u32_e32 v78, 19, v148
	v_perm_b32 v76, v94, v76, s65
	v_cndmask_b32_e64 v77, v224, 0, vcc
	v_cmp_gt_i32_e32 vcc, v78, v1
	s_nop 1
	v_cndmask_b32_e64 v95, v224, 0, vcc
	v_cmp_gt_i32_e32 vcc, v79, v1
	v_add_u32_e32 v79, 21, v148
	v_perm_b32 v77, v95, v77, s65
	v_cndmask_b32_e64 v78, v224, 0, vcc
	v_cmp_gt_i32_e32 vcc, v79, v1
	s_nop 1
	v_cndmask_b32_e64 v97, v224, 0, vcc
	v_cmp_gt_i32_e32 vcc, v96, v1
	v_add_u32_e32 v96, 23, v148
	v_perm_b32 v78, v97, v78, s65
	v_cndmask_b32_e64 v79, v224, 0, vcc
	v_cmp_gt_i32_e32 vcc, v96, v1
	s_nop 1
	v_cndmask_b32_e64 v96, v224, 0, vcc
	v_perm_b32 v79, v96, v79, s65
	s_nop 1
	v_mfma_f32_32x32x16_bf16 v[20:35], v[36:39], v[76:79], v[20:35]
	v_add_u32_e32 v36, 32, v148
	v_cmp_gt_i32_e32 vcc, v36, v1
	v_add_u32_e32 v37, 33, v148
	v_add_u32_e32 v38, 34, v148
	v_cndmask_b32_e64 v36, v224, 0, vcc
	v_cmp_gt_i32_e32 vcc, v37, v1
	v_add_u32_e32 v39, 36, v148
	s_waitcnt lgkmcnt(4)
	v_mfma_f32_32x32x16_bf16 v[20:35], v[80:83], v[76:79], v[20:35]
	v_cndmask_b32_e64 v76, v224, 0, vcc
	v_cmp_gt_i32_e32 vcc, v38, v1
	v_add_u32_e32 v38, 35, v148
	v_add_u32_e32 v78, 38, v148
	v_cndmask_b32_e64 v37, v224, 0, vcc
	v_cmp_gt_i32_e32 vcc, v38, v1
	v_perm_b32 v36, v76, v36, s65
	v_mov_b32_e32 v81, v180
	v_cndmask_b32_e64 v77, v224, 0, vcc
	v_cmp_gt_i32_e32 vcc, v39, v1
	v_add_u32_e32 v39, 37, v148
	v_perm_b32 v37, v77, v37, s65
	v_cndmask_b32_e64 v38, v224, 0, vcc
	v_cmp_gt_i32_e32 vcc, v39, v1
	s_nop 1
	v_cndmask_b32_e64 v79, v224, 0, vcc
	v_cmp_gt_i32_e32 vcc, v78, v1
	v_add_u32_e32 v78, 39, v148
	v_perm_b32 v38, v79, v38, s65
	v_cndmask_b32_e64 v39, v224, 0, vcc
	v_cmp_gt_i32_e32 vcc, v78, v1
	s_nop 1
	v_cndmask_b32_e64 v78, v224, 0, vcc
	v_perm_b32 v39, v78, v39, s65
	s_nop 1
	v_mfma_f32_32x32x16_bf16 v[20:35], v[40:43], v[36:39], v[20:35]
	v_add_u32_e32 v42, 54, v148
	s_waitcnt lgkmcnt(2)
	v_mfma_f32_32x32x16_bf16 v[20:35], v[86:89], v[36:39], v[20:35]
	v_add_u32_e32 v36, 48, v148
	v_cmp_gt_i32_e32 vcc, v36, v1
	v_add_u32_e32 v37, 49, v148
	v_add_u32_e32 v38, 50, v148
	v_cndmask_b32_e64 v36, v224, 0, vcc
	v_cmp_gt_i32_e32 vcc, v37, v1
	v_add_u32_e32 v39, 52, v148
	v_and_b32_e32 v89, 31, v81
	v_cndmask_b32_e64 v40, v224, 0, vcc
	v_cmp_gt_i32_e32 vcc, v38, v1
	v_add_u32_e32 v38, 51, v148
	v_perm_b32 v36, v40, v36, s65
	v_cndmask_b32_e64 v37, v224, 0, vcc
	v_cmp_gt_i32_e32 vcc, v38, v1
	v_ashrrev_i32_e32 v88, 5, v81
	v_lshl_add_u32 v178, v88, 2, s91
	v_cndmask_b32_e64 v41, v224, 0, vcc
	v_cmp_gt_i32_e32 vcc, v39, v1
	v_add_u32_e32 v39, 53, v148
	v_perm_b32 v37, v41, v37, s65
	v_cndmask_b32_e64 v38, v224, 0, vcc
	v_cmp_gt_i32_e32 vcc, v39, v1
	v_lshlrev_b32_e32 v40, 2, v178
	v_add_u32_e32 v185, 16, v178
	v_cndmask_b32_e64 v43, v224, 0, vcc
	v_cmp_gt_i32_e32 vcc, v42, v1
	v_add_u32_e32 v42, 55, v148
	v_perm_b32 v38, v43, v38, s65
	v_cndmask_b32_e64 v39, v224, 0, vcc
	v_cmp_gt_i32_e32 vcc, v42, v1
	v_add_u32_e32 v189, 24, v178
	s_nop 0
	v_cndmask_b32_e64 v1, v224, 0, vcc
	v_perm_b32 v39, v1, v39, s65
	v_bitop3_b32 v1, v89, 63, s43 bitop3:0x36
	s_nop 0
	v_mfma_f32_32x32x16_bf16 v[20:35], v[48:51], v[36:39], v[20:35]
	s_waitcnt lgkmcnt(0)
	v_mfma_f32_32x32x16_bf16 v[20:35], v[90:93], v[36:39], v[20:35]
	v_or_b32_e32 v36, s43, v89
	v_cndmask_b32_e64 v1, v1, v36, s[36:37]
	v_lshl_add_u32 v37, v1, 2, 0
	v_add_u32_e32 v37, 0x24000, v37
	ds_read_b32 v80, v37
	v_mov_b32_e32 v37, s30
	v_mov_b32_e32 v38, s27
	v_cmp_gt_u32_e32 vcc, 32, v1
	v_mul_u32_u24_e32 v188, 0x90, v36
	s_nop 2
	v_sub_f32_e32 v87, v23, v47
	v_cndmask_b32_e32 v37, v37, v38, vcc
	v_lshlrev_b32_e32 v38, 8, v1
	v_and_b32_e32 v38, 0x1f00, v38
	v_add_u32_e32 v179, v37, v38
	v_cndmask_b32_e32 v37, v98, v99, vcc
	v_add_u32_e32 v181, v37, v38
	v_add_u32_e32 v36, v179, v40
	v_add_u32_e32 v41, v181, v40
	v_add_u32_e32 v40, 0, v40
	ds_read_b128 v[48:51], v41
	v_add_u32_e32 v182, 0x24700, v40
	ds_read_b128 v[36:39], v36
	v_add_u32_e32 v183, 0x24800, v40
	ds_read_b128 v[76:79], v182
	ds_read_b128 v[90:93], v183
	v_sub_f32_e32 v47, v22, v46
	v_sub_f32_e32 v46, v21, v45
	v_sub_f32_e32 v45, v20, v44
	v_exp_f32_e32 v44, v20
	v_exp_f32_e32 v82, v45
	v_exp_f32_e64 v20, -v20
	v_exp_f32_e32 v45, v21
	v_exp_f32_e32 v83, v46
	v_exp_f32_e64 v21, -v21
	v_exp_f32_e32 v46, v22
	v_exp_f32_e32 v86, v47
	v_exp_f32_e32 v47, v23
	v_exp_f32_e32 v87, v87
	s_waitcnt lgkmcnt(1)
	v_pk_mul_f32 v[78:79], v[50:51], v[78:79]
	v_pk_mul_f32 v[76:77], v[48:49], v[76:77]
	v_exp_f32_e64 v22, -v22
	v_exp_f32_e64 v23, -v23
	v_pk_mul_f32 v[94:95], v[80:81], v[78:79] op_sel_hi:[0,1]
	v_pk_mul_f32 v[96:97], v[80:81], v[76:77] op_sel_hi:[0,1]
	v_pk_add_f32 v[76:77], v[54:55], -1.0 op_sel_hi:[1,0]
	v_pk_add_f32 v[78:79], v[52:53], -1.0 op_sel_hi:[1,0]
	s_waitcnt lgkmcnt(0)
	v_pk_fma_f32 v[76:77], v[76:77], v[92:93], 1.0 op_sel_hi:[1,1,0]
	v_pk_fma_f32 v[78:79], v[78:79], v[90:91], 1.0 op_sel_hi:[1,1,0]
	v_pk_mul_f32 v[76:77], v[50:51], v[76:77]
	v_pk_mul_f32 v[78:79], v[48:49], v[78:79]
	v_pk_mul_f32 v[50:51], v[52:53], v[96:97]
	v_pk_mul_f32 v[148:149], v[38:39], v[46:47]
	v_pk_mul_f32 v[154:155], v[36:37], v[44:45]
	v_pk_mul_f32 v[48:49], v[54:55], v[94:95]
	v_pk_mul_f32 v[152:153], v[20:21], v[78:79]
	v_pk_mul_f32 v[52:53], v[86:87], v[94:95]
	v_pk_mul_f32 v[54:55], v[82:83], v[96:97]
	v_pk_mul_f32 v[20:21], v[20:21], v[50:51]
	v_lshlrev_b32_e32 v50, 1, v178
	v_add_u32_e32 v184, 0x24900, v40
	v_pk_mul_f32 v[150:151], v[22:23], v[76:77]
	v_pk_mul_f32 v[22:23], v[22:23], v[48:49]
	v_cvt_pk_bf16_f32 v48, v54, v55
	v_cvt_pk_bf16_f32 v49, v52, v53
	v_add3_u32 v52, v50, v188, s76
	v_cvt_pk_bf16_f32 v50, v154, v155
	v_cvt_pk_bf16_f32 v51, v148, v149
	v_add_u32_e32 v98, 8, v178
	ds_read_b128 v[40:43], v184
	ds_write2st64_b64 v52, v[48:49], v[50:51] offset1:18
	v_cvt_pk_bf16_f32 v20, v20, v21
	v_cvt_pk_bf16_f32 v21, v22, v23
	v_cvt_pk_bf16_f32 v22, v152, v153
	v_cvt_pk_bf16_f32 v23, v150, v151
	v_lshlrev_b32_e32 v48, 2, v98
	ds_write2st64_b64 v52, v[20:21], v[22:23] offset0:36 offset1:54
	v_add_u32_e32 v20, v179, v48
	v_add_u32_e32 v48, v181, v48
	ds_read_b128 v[20:23], v20
	ds_read_b128 v[90:93], v48
	ds_read_b128 v[94:97], v182 offset:32
	ds_read_b128 v[156:159], v183 offset:32
	ds_read_b128 v[48:51], v184 offset:32
	v_sub_f32_e32 v82, v27, v85
	v_sub_f32_e32 v55, v26, v84
	v_sub_f32_e32 v54, v25, v75
	v_sub_f32_e32 v53, v24, v74
	v_exp_f32_e32 v52, v24
	v_exp_f32_e32 v84, v53
	v_exp_f32_e32 v53, v25
	v_exp_f32_e32 v85, v54
	v_exp_f32_e32 v54, v26
	v_exp_f32_e32 v86, v55
	v_exp_f32_e64 v26, -v26
	v_exp_f32_e32 v55, v27
	v_exp_f32_e32 v87, v82
	v_exp_f32_e64 v27, -v27
	s_waitcnt lgkmcnt(2)
	v_pk_mul_f32 v[74:75], v[92:93], v[96:97]
	v_exp_f32_e64 v24, -v24
	v_exp_f32_e64 v25, -v25
	v_pk_mul_f32 v[82:83], v[90:91], v[94:95]
	v_pk_mul_f32 v[94:95], v[80:81], v[74:75] op_sel_hi:[0,1]
	v_pk_add_f32 v[74:75], v[58:59], -1.0 op_sel_hi:[1,0]
	v_pk_mul_f32 v[96:97], v[80:81], v[82:83] op_sel_hi:[0,1]
	v_pk_add_f32 v[82:83], v[56:57], -1.0 op_sel_hi:[1,0]
	s_waitcnt lgkmcnt(1)
	v_pk_fma_f32 v[74:75], v[74:75], v[158:159], 1.0 op_sel_hi:[1,1,0]
	v_pk_fma_f32 v[82:83], v[82:83], v[156:157], 1.0 op_sel_hi:[1,1,0]
	v_pk_mul_f32 v[74:75], v[92:93], v[74:75]
	v_pk_mul_f32 v[58:59], v[58:59], v[94:95]
	v_pk_mul_f32 v[82:83], v[90:91], v[82:83]
	v_pk_mul_f32 v[158:159], v[54:55], v[22:23]
	v_pk_mul_f32 v[164:165], v[52:53], v[20:21]
	v_pk_mul_f32 v[56:57], v[56:57], v[96:97]
	v_pk_mul_f32 v[156:157], v[26:27], v[74:75]
	v_pk_mul_f32 v[86:87], v[86:87], v[94:95]
	v_pk_mul_f32 v[84:85], v[84:85], v[96:97]
	v_pk_mul_f32 v[26:27], v[26:27], v[58:59]
	v_lshlrev_b32_e32 v58, 1, v98
	v_pk_mul_f32 v[166:167], v[24:25], v[82:83]
	v_pk_mul_f32 v[24:25], v[24:25], v[56:57]
	v_cvt_pk_bf16_f32 v56, v84, v85
	v_cvt_pk_bf16_f32 v57, v86, v87
	v_add3_u32 v84, v58, v188, s76
	v_cvt_pk_bf16_f32 v58, v164, v165
	v_cvt_pk_bf16_f32 v59, v158, v159
	ds_write2st64_b64 v84, v[56:57], v[58:59] offset1:18
	v_cvt_pk_bf16_f32 v24, v24, v25
	v_cvt_pk_bf16_f32 v25, v26, v27
	v_cvt_pk_bf16_f32 v26, v166, v167
	v_cvt_pk_bf16_f32 v27, v156, v157
	v_lshlrev_b32_e32 v56, 2, v185
	ds_write2st64_b64 v84, v[24:25], v[26:27] offset0:36 offset1:54
	v_add_u32_e32 v24, v179, v56
	v_add_u32_e32 v56, v181, v56
	ds_read_b128 v[24:27], v24
	ds_read_b128 v[90:93], v56
	ds_read_b128 v[84:87], v182 offset:64
	ds_read_b128 v[94:97], v183 offset:64
	ds_read_b128 v[56:59], v184 offset:64
	v_sub_f32_e32 v160, v31, v63
	v_sub_f32_e32 v63, v30, v62
	v_sub_f32_e32 v62, v29, v61
	v_sub_f32_e32 v61, v28, v60
	v_exp_f32_e32 v60, v28
	v_exp_f32_e32 v98, v61
	v_exp_f32_e32 v61, v29
	v_exp_f32_e32 v99, v62
	v_exp_f32_e32 v62, v30
	v_exp_f32_e32 v168, v63
	v_exp_f32_e64 v30, -v30
	v_exp_f32_e32 v63, v31
	v_exp_f32_e32 v169, v160
	v_exp_f32_e64 v31, -v31
	s_waitcnt lgkmcnt(2)
	v_pk_mul_f32 v[84:85], v[90:91], v[84:85]
	v_exp_f32_e64 v28, -v28
	v_exp_f32_e64 v29, -v29
	v_pk_mul_f32 v[86:87], v[92:93], v[86:87]
	v_pk_mul_f32 v[176:177], v[80:81], v[84:85] op_sel_hi:[0,1]
	v_pk_add_f32 v[84:85], v[66:67], -1.0 op_sel_hi:[1,0]
	v_pk_mul_f32 v[172:173], v[80:81], v[86:87] op_sel_hi:[0,1]
	v_pk_add_f32 v[86:87], v[64:65], -1.0 op_sel_hi:[1,0]
	s_waitcnt lgkmcnt(1)
	v_pk_fma_f32 v[84:85], v[84:85], v[96:97], 1.0 op_sel_hi:[1,1,0]
	v_pk_fma_f32 v[86:87], v[86:87], v[94:95], 1.0 op_sel_hi:[1,1,0]
	v_pk_mul_f32 v[84:85], v[92:93], v[84:85]
	v_pk_mul_f32 v[66:67], v[66:67], v[172:173]
	v_pk_mul_f32 v[86:87], v[90:91], v[86:87]
	v_pk_mul_f32 v[160:161], v[62:63], v[26:27]
	v_pk_mul_f32 v[174:175], v[60:61], v[24:25]
	v_pk_mul_f32 v[64:65], v[64:65], v[176:177]
	v_pk_mul_f32 v[162:163], v[30:31], v[84:85]
	v_pk_mul_f32 v[90:91], v[168:169], v[172:173]
	v_pk_mul_f32 v[92:93], v[98:99], v[176:177]
	v_pk_mul_f32 v[30:31], v[30:31], v[66:67]
	v_lshlrev_b32_e32 v66, 1, v185
	v_pk_mul_f32 v[170:171], v[28:29], v[86:87]
	v_pk_mul_f32 v[28:29], v[28:29], v[64:65]
	v_cvt_pk_bf16_f32 v64, v92, v93
	v_cvt_pk_bf16_f32 v65, v90, v91
	v_add3_u32 v90, v66, v188, s76
	v_cvt_pk_bf16_f32 v66, v174, v175
	v_cvt_pk_bf16_f32 v67, v160, v161
	ds_write2st64_b64 v90, v[64:65], v[66:67] offset1:18
	v_cvt_pk_bf16_f32 v28, v28, v29
	v_cvt_pk_bf16_f32 v29, v30, v31
	v_cvt_pk_bf16_f32 v30, v170, v171
	v_cvt_pk_bf16_f32 v31, v162, v163
	v_lshlrev_b32_e32 v64, 2, v189
	ds_write2st64_b64 v90, v[28:29], v[30:31] offset0:36 offset1:54
	v_add_u32_e32 v28, v179, v64
	v_add_u32_e32 v64, v181, v64
	ds_read_b128 v[28:31], v28
	ds_read_b128 v[90:93], v64
	ds_read_b128 v[94:97], v182 offset:96
	ds_read_b128 v[176:179], v183 offset:96
	ds_read_b128 v[64:67], v184 offset:96
	v_sub_f32_e32 v168, v35, v71
	v_sub_f32_e32 v71, v34, v70
	v_sub_f32_e32 v70, v33, v69
	v_sub_f32_e32 v69, v32, v68
	v_exp_f32_e32 v68, v32
	v_exp_f32_e32 v98, v69
	v_exp_f32_e64 v182, -v32
	v_exp_f32_e32 v69, v33
	v_exp_f32_e32 v99, v70
	v_exp_f32_e64 v183, -v33
	v_exp_f32_e32 v70, v34
	v_exp_f32_e32 v184, v71
	v_exp_f32_e64 v186, -v34
	v_exp_f32_e32 v71, v35
	v_exp_f32_e32 v185, v168
	v_exp_f32_e64 v187, -v35
	s_waitcnt lgkmcnt(2)
	v_pk_mul_f32 v[32:33], v[92:93], v[96:97]
	v_pk_mul_f32 v[34:35], v[90:91], v[94:95]
	v_pk_mul_f32 v[94:95], v[80:81], v[32:33] op_sel_hi:[0,1]
	v_pk_mul_f32 v[96:97], v[80:81], v[34:35] op_sel_hi:[0,1]
	v_pk_add_f32 v[32:33], v[72:73], -1.0 op_sel_hi:[1,0]
	v_pk_add_f32 v[34:35], v[2:3], -1.0 op_sel_hi:[1,0]
	s_waitcnt lgkmcnt(1)
	v_pk_fma_f32 v[32:33], v[32:33], v[178:179], 1.0 op_sel_hi:[1,1,0]
	v_pk_fma_f32 v[34:35], v[34:35], v[176:177], 1.0 op_sel_hi:[1,1,0]
	v_pk_mul_f32 v[32:33], v[92:93], v[32:33]
	v_pk_mul_f32 v[34:35], v[90:91], v[34:35]
	v_pk_mul_f32 v[72:73], v[72:73], v[94:95]
	v_pk_mul_f32 v[2:3], v[2:3], v[96:97]
	v_pk_mul_f32 v[172:173], v[70:71], v[30:31]
	v_pk_mul_f32 v[176:177], v[68:69], v[28:29]
	v_pk_mul_f32 v[168:169], v[186:187], v[32:33]
	v_pk_mul_f32 v[178:179], v[182:183], v[34:35]
	v_pk_mul_f32 v[90:91], v[184:185], v[94:95]
	v_pk_mul_f32 v[92:93], v[98:99], v[96:97]
	v_pk_mul_f32 v[72:73], v[186:187], v[72:73]
	v_pk_mul_f32 v[2:3], v[182:183], v[2:3]
	v_lshlrev_b32_e32 v80, 1, v189
	v_cmp_eq_u32_e32 vcc, 31, v89
	v_cvt_pk_bf16_f32 v92, v92, v93
	v_cvt_pk_bf16_f32 v93, v90, v91
	v_add3_u32 v80, v80, v188, s76
	v_cvt_pk_bf16_f32 v90, v176, v177
	v_cvt_pk_bf16_f32 v91, v172, v173
	v_cvt_pk_bf16_f32 v2, v2, v3
	v_cvt_pk_bf16_f32 v3, v72, v73
	v_cvt_pk_bf16_f32 v72, v178, v179
	v_cvt_pk_bf16_f32 v73, v168, v169
	s_and_b64 s[38:39], s[62:63], vcc
	ds_write2st64_b64 v80, v[92:93], v[90:91] offset1:18
	ds_write2st64_b64 v80, v[2:3], v[72:73] offset0:36 offset1:54
	s_and_saveexec_b64 s[30:31], s[38:39]
	s_cbranch_execz .LBB0_85
	v_readlane_b32 s27, v255, 10
	s_nop 1
	v_lshl_add_u32 v2, v88, 4, s27
	ds_write_b128 v2, v[44:47]
	ds_write_b128 v2, v[52:55] offset:32
	ds_write_b128 v2, v[60:63] offset:64
	ds_write_b128 v2, v[68:71] offset:96

.LBB0_105:
	s_waitcnt lgkmcnt(0)
	s_barrier
	s_bitcmp1_b32 s60, 0
	s_cbranch_scc1 .Lstg_4
	s_sleep 4
.Lstg_4:
	v_mov_b32_e32 v2, v180
	s_lshr_b32 s68, s50, 6
	v_cmp_lt_u32_e32 vcc, 31, v2
	s_or_b64 s[38:39], s[96:97], vcc
	s_and_saveexec_b64 vcc, s[38:39]
	s_xor_b64 s[38:39], exec, vcc
	s_lshl_b32 s57, s68, 12
	s_or_saveexec_b64 s[38:39], s[38:39]
	s_and_b32 s50, s50, 63
	s_lshl_b32 s56, s50, 6
	v_mov_b32_e32 v1, s57
	s_xor_b64 exec, exec, s[38:39]
	s_cbranch_execz .LBB0_109
	v_or_b32_e32 v1, s43, v2
	v_bitop3_b32 v2, v2, 63, s43 bitop3:0x36
	v_cndmask_b32_e64 v1, v2, v1, s[36:37]
	v_readlane_b32 s40, v255, 11
	v_mov_b32_e32 v21, v0
	v_readlane_b32 vcc_lo, v255, 13
	v_lshl_add_u32 v2, v1, 2, s40
	s_waitcnt lgkmcnt(0)
	ds_read2st64_b32 v[2:3], v2 offset1:1
	s_lshl_b32 s40, s68, 12
	s_or_b32 s41, s40, s56
	v_or_b32_e32 v20, s41, v1
	v_readlane_b32 vcc_hi, v255, 14
	s_waitcnt lgkmcnt(0)
	v_add_f32_e32 v1, v2, v3
	v_lshlrev_b64 v[2:3], 5, v[20:21]
	v_lshl_add_u64 v[2:3], vcc, 0, v[2:3]
	global_store_dword v[2:3], v1, off
	v_mov_b32_e32 v1, s40
.LBB0_109:
	s_or_b64 exec, exec, s[38:39]
	v_mov_b32_e32 v2, v180
	v_mov_b32_e32 v20, s76
	s_waitcnt lgkmcnt(0)
	v_and_b32_e32 v3, 31, v2
	v_ashrrev_i32_e32 v2, 5, v2
	v_or_b32_e32 v90, s43, v3
	v_or_b32_e32 v3, s91, v3
	v_mad_u32_u24 v91, v90, s64, v20
	v_lshlrev_b32_e32 v20, 4, v2
	v_mul_u32_u24_e32 v3, 0x90, v3
	v_mov_b32_e32 v53, 0
	v_add_u32_e32 v21, v91, v20
	v_add3_u32 v3, s76, v3, v20
	ds_read_b128 v[36:39], v21
	ds_read_b128 v[54:57], v21 offset:32
	ds_read_b128 v[58:61], v21 offset:64
	ds_read_b128 v[62:65], v21 offset:96
	ds_read_b128 v[20:23], v3 offset:18432
	ds_read_b128 v[66:69], v3 offset:18464
	ds_read_b128 v[70:73], v3 offset:18496
	ds_read_b128 v[74:77], v3 offset:18528
	ds_read_b128 v[40:43], v3 offset:27648
	ds_read_b128 v[78:81], v3 offset:27680
	ds_read_b128 v[82:85], v3 offset:27712
	ds_read_b128 v[86:89], v3 offset:27744
	v_mov_b32_e32 v52, 0
	s_waitcnt lgkmcnt(7)
	v_mfma_f32_32x32x16_bf16 v[20:35], v[20:23], v[36:39], 0
	v_lshl_add_u32 v3, v2, 2, s91
	v_cmp_lt_i32_e32 vcc, v3, v90
	v_lshlrev_b32_e32 v2, 3, v2
	v_readlane_b32 s38, v252, 16
	s_waitcnt lgkmcnt(3)
	v_mfma_f32_32x32x16_bf16 v[36:51], v[40:43], v[36:39], 0
	v_mfma_f32_32x32x16_bf16 v[20:35], v[66:69], v[54:57], v[20:35]
	s_waitcnt lgkmcnt(2)
	v_mfma_f32_32x32x16_bf16 v[36:51], v[78:81], v[54:57], v[36:51]
	v_or_b32_e32 v54, 1, v3
	v_mfma_f32_32x32x16_bf16 v[20:35], v[70:73], v[58:61], v[20:35]
	v_mov_b32_e32 v72, 0
	v_mov_b32_e32 v73, 0
	s_waitcnt lgkmcnt(1)
	v_mfma_f32_32x32x16_bf16 v[36:51], v[82:85], v[58:61], v[36:51]
	v_mfma_f32_32x32x16_bf16 v[20:35], v[74:77], v[62:65], v[20:35]
	v_mov_b32_e32 v74, 0
	v_mov_b32_e32 v75, 0
	s_waitcnt lgkmcnt(0)
	v_mfma_f32_32x32x16_bf16 v[36:51], v[86:89], v[62:65], v[36:51]
	s_nop 7
	v_cndmask_b32_e64 v20, 0, -v20, vcc
	s_nop 2
	v_cndmask_b32_e32 v36, 0, v36, vcc
	v_cmp_lt_i32_e32 vcc, v54, v90
	v_or_b32_e32 v54, 2, v3
	s_nop 0
	v_cndmask_b32_e64 v21, 0, -v21, vcc
	v_cndmask_b32_e32 v37, 0, v37, vcc
	v_cmp_lt_i32_e32 vcc, v54, v90
	v_or_b32_e32 v54, 3, v3
	s_nop 0
	v_cndmask_b32_e64 v22, 0, -v22, vcc
	v_cndmask_b32_e32 v38, 0, v38, vcc
	v_cmp_lt_i32_e32 vcc, v54, v90
	v_add_u32_e32 v54, 8, v3
	s_nop 0
	v_cndmask_b32_e64 v23, 0, -v23, vcc
	v_cndmask_b32_e32 v39, 0, v39, vcc
	v_cmp_lt_i32_e32 vcc, v54, v90
	v_add_u32_e32 v54, 9, v3
	s_nop 0
	v_cndmask_b32_e64 v24, 0, -v24, vcc
	v_cndmask_b32_e32 v40, 0, v40, vcc
	v_cmp_lt_i32_e32 vcc, v54, v90
	v_add_u32_e32 v54, 10, v3
	s_nop 0
	v_cndmask_b32_e64 v25, 0, -v25, vcc
	v_cndmask_b32_e32 v41, 0, v41, vcc
	v_cmp_lt_i32_e32 vcc, v54, v90
	v_add_u32_e32 v54, 11, v3
	s_nop 0
	v_cndmask_b32_e64 v26, 0, -v26, vcc
	v_cndmask_b32_e32 v42, 0, v42, vcc
	v_cmp_lt_i32_e32 vcc, v54, v90
	v_add_u32_e32 v54, 16, v3
	s_nop 0
	v_cndmask_b32_e64 v27, 0, -v27, vcc
	v_cndmask_b32_e32 v43, 0, v43, vcc
	v_cmp_lt_i32_e32 vcc, v54, v90
	v_add_u32_e32 v54, 17, v3
	s_nop 0
	v_cndmask_b32_e64 v28, 0, -v28, vcc
	v_cndmask_b32_e32 v44, 0, v44, vcc
	v_cmp_lt_i32_e32 vcc, v54, v90
	v_add_u32_e32 v54, 18, v3
	s_nop 0
	v_cndmask_b32_e64 v29, 0, -v29, vcc
	v_cndmask_b32_e32 v45, 0, v45, vcc
	v_cmp_lt_i32_e32 vcc, v54, v90
	v_add_u32_e32 v54, 19, v3
	s_nop 0
	v_cndmask_b32_e64 v30, 0, -v30, vcc
	v_cndmask_b32_e32 v46, 0, v46, vcc
	v_cmp_lt_i32_e32 vcc, v54, v90
	v_add_u32_e32 v54, 24, v3
	s_nop 0
	v_cndmask_b32_e64 v31, 0, -v31, vcc
	v_cndmask_b32_e32 v47, 0, v47, vcc
	v_cmp_lt_i32_e32 vcc, v54, v90
	v_add_u32_e32 v54, 25, v3
	s_nop 0
	v_cndmask_b32_e64 v32, 0, -v32, vcc
	v_cndmask_b32_e32 v48, 0, v48, vcc
	v_cmp_lt_i32_e32 vcc, v54, v90
	v_add_u32_e32 v54, 26, v3
	v_add_u32_e32 v3, 27, v3
	v_cndmask_b32_e64 v33, 0, -v33, vcc
	v_cndmask_b32_e32 v49, 0, v49, vcc
	v_cmp_lt_i32_e32 vcc, v54, v90
	v_add3_u32 v54, v91, v2, s28
	v_cvt_pk_bf16_f32 v2, v20, v21
	v_cndmask_b32_e64 v34, 0, -v34, vcc
	v_cndmask_b32_e32 v50, 0, v50, vcc
	v_cmp_lt_i32_e32 vcc, v3, v90
	v_cvt_pk_bf16_f32 v3, v22, v23
	v_cvt_pk_bf16_f32 v20, v24, v25
	v_cndmask_b32_e64 v35, 0, -v35, vcc
	v_cvt_pk_bf16_f32 v21, v26, v27
	v_add_u32_e32 v22, 0x9000, v54
	ds_write2_b64 v22, v[2:3], v[20:21] offset1:2
	v_cvt_pk_bf16_f32 v2, v28, v29
	v_cvt_pk_bf16_f32 v3, v30, v31
	v_cvt_pk_bf16_f32 v20, v32, v33
	v_cvt_pk_bf16_f32 v21, v34, v35
	ds_write2_b64 v22, v[2:3], v[20:21] offset0:4 offset1:6
	v_cvt_pk_bf16_f32 v2, v53, v53
	v_mov_b32_e32 v3, v2
	v_add_u32_e32 v20, 0xb000, v54
	v_cndmask_b32_e32 v51, 0, v51, vcc
	ds_write2_b64 v20, v[2:3], v[2:3] offset0:128 offset1:130
	ds_write2_b64 v20, v[2:3], v[2:3] offset0:132 offset1:134
	v_cvt_pk_bf16_f32 v2, v36, v37
	v_cvt_pk_bf16_f32 v3, v38, v39
	v_cvt_pk_bf16_f32 v20, v40, v41
	v_cvt_pk_bf16_f32 v21, v42, v43
	v_add_u32_e32 v22, 0xd800, v54
	ds_write2_b64 v22, v[2:3], v[20:21] offset1:2
	v_cvt_pk_bf16_f32 v2, v44, v45
	v_cvt_pk_bf16_f32 v3, v46, v47
	v_cvt_pk_bf16_f32 v20, v48, v49
	v_cvt_pk_bf16_f32 v21, v50, v51
	ds_write2_b64 v22, v[2:3], v[20:21] offset0:4 offset1:6
	v_mov_b32_e32 v2, v180
	s_waitcnt lgkmcnt(0)
	s_barrier
	s_bitcmp1_b32 s60, 0
	s_cbranch_scc1 .Lstg_5
	s_sleep 4
.Lstg_5:
	v_mov_b32_e32 v23, v0
	v_add_u32_e32 v3, s42, v2
	v_lshrrev_b32_e32 v20, 2, v3
	v_bfe_u32 v3, v3, 2, 6
	v_lshlrev_b32_e32 v21, 4, v2
	v_bitop3_b32 v2, v20, 63, v20 bitop3:0xc
	v_cndmask_b32_e64 v2, v2, v3, s[36:37]
	v_or_b32_e32 v20, s56, v2
	v_or_b32_e32 v2, v20, v1
	v_mov_b32_e32 v3, v0
	v_and_or_b32 v1, v21, 48, s38
	v_lshlrev_b64 v[2:3], 10, v[2:3]
	v_lshl_add_u64 v[2:3], s[48:49], 0, v[2:3]
	v_lshlrev_b32_e32 v22, 1, v1
	v_lshl_add_u64 v[2:3], v[2:3], 0, v[22:23]
	global_load_dwordx4 v[68:71], v[2:3], off
	v_cmp_ne_u32_e32 vcc, 0, v20
	s_and_saveexec_b64 s[38:39], vcc
	s_cbranch_execz .LBB0_111
	global_load_dwordx4 v[72:75], v[2:3], off offset:-1024

.Lstg_6:
	v_cndmask_b32_e64 v2, 0, 1, s[80:81]
	v_mov_b32_e32 v1, v180
	v_cmp_ne_u32_e64 s[38:39], 1, v2
	s_andn2_b64 vcc, exec, s[80:81]
	s_cbranch_vccnz .LBB0_123
	v_and_b32_e32 v18, 31, v1
	v_ashrrev_i32_e32 v19, 5, v1
	v_or_b32_e32 v2, s43, v18
	v_mul_u32_u24_e32 v2, 0x90, v2
	v_lshlrev_b32_e32 v3, 4, v19
	v_lshrrev_b32_e32 v4, 2, v1
	v_add3_u32 v2, s0, v2, v3
	v_and_b32_e32 v3, 16, v1
	v_and_b32_e32 v5, 0xffffff8, v4
	v_lshlrev_b32_e32 v1, 2, v1
	v_add_u32_e32 v5, s43, v5
	v_and_b32_e32 v1, 12, v1
	v_and_or_b32 v4, v4, 3, v5
	v_or3_b32 v1, v3, v1, s43
	v_mul_lo_u32 v4, v4, s64
	v_lshlrev_b32_e32 v1, 1, v1
	v_add3_u32 v1, s76, v4, v1
	ds_read_b128 v[2:5], v2 offset:36864
	ds_read_b64_tr_b16 v[6:7], v1 offset:46080
	ds_read_b64_tr_b16 v[8:9], v1 offset:46656
	v_cmp_lt_u32_e32 vcc, 15, v18
	v_mul_u32_u24_e32 v1, 0x90, v18
	v_lshlrev_b32_e32 v18, 3, v19
	s_waitcnt lgkmcnt(2)
	v_cndmask_b32_e32 v5, 0, v5, vcc
	v_cndmask_b32_e32 v4, 0, v4, vcc
	v_cndmask_b32_e32 v3, 0, v3, vcc
	v_cndmask_b32_e32 v2, 0, v2, vcc
	v_add3_u32 v1, s1, v1, v18
	s_waitcnt lgkmcnt(0)
	v_mfma_f32_32x32x16_bf16 v[2:17], v[6:9], v[2:5], 0
	s_nop 11
	v_cvt_pk_bf16_f32 v2, v2, v3
	v_cvt_pk_bf16_f32 v3, v4, v5
	v_cvt_pk_bf16_f32 v4, v6, v7
	v_cvt_pk_bf16_f32 v5, v8, v9
	ds_write2_b64 v1, v[2:3], v[4:5] offset0:8 offset1:10
	v_cvt_pk_bf16_f32 v2, v10, v11
	v_cvt_pk_bf16_f32 v3, v12, v13
	v_cvt_pk_bf16_f32 v4, v14, v15
	v_cvt_pk_bf16_f32 v5, v16, v17
	ds_write2_b64 v1, v[2:3], v[4:5] offset0:12 offset1:14

.Lstg_7:
	v_mov_b32_e32 v1, v180
	s_and_b64 vcc, exec, s[38:39]
	s_cbranch_vccnz .LBB0_125
	v_and_or_b32 v2, v1, 31, s43
	v_mov_b32_e32 v3, s0
	v_ashrrev_i32_e32 v18, 5, v1
	v_mad_u32_u24 v19, v2, s64, v3
	v_and_b32_e32 v12, 16, v1
	v_lshrrev_b32_e32 v13, 2, v1
	v_lshlrev_b32_e32 v1, 2, v1
	v_lshl_add_u32 v2, v18, 3, v19
	v_and_b32_e32 v13, 0xffffffb, v13
	v_and_or_b32 v1, v1, 12, v12
	v_add_u32_e32 v84, 0xb000, v2
	v_lshlrev_b32_e32 v1, 1, v1
	v_mul_lo_u32 v12, v13, s64
	ds_read2_b64 v[6:9], v84 offset0:128 offset1:130
	ds_read2_b64 v[14:17], v84 offset0:132 offset1:134
	v_add3_u32 v1, s1, v1, v12
	v_lshl_add_u32 v18, v18, 4, v19
	ds_read_b64_tr_b16 v[76:77], v1 offset:64
	ds_read_b64_tr_b16 v[78:79], v1 offset:640
	ds_read_b128 v[80:83], v18 offset:46080
	s_waitcnt lgkmcnt(4)
	v_lshlrev_b32_e32 v2, 16, v6
	v_and_b32_e32 v3, 0xffff0000, v6
	v_lshlrev_b32_e32 v4, 16, v7
	v_and_b32_e32 v5, 0xffff0000, v7
	v_lshlrev_b32_e32 v6, 16, v8
	v_and_b32_e32 v7, 0xffff0000, v8
	v_lshlrev_b32_e32 v8, 16, v9
	v_and_b32_e32 v9, 0xffff0000, v9
	s_waitcnt lgkmcnt(3)
	v_lshlrev_b32_e32 v10, 16, v14
	v_and_b32_e32 v11, 0xffff0000, v14
	v_lshlrev_b32_e32 v12, 16, v15
	v_and_b32_e32 v13, 0xffff0000, v15
	v_lshlrev_b32_e32 v14, 16, v16
	v_and_b32_e32 v15, 0xffff0000, v16
	v_lshlrev_b32_e32 v16, 16, v17
	v_and_b32_e32 v17, 0xffff0000, v17
	s_waitcnt lgkmcnt(0)
	s_nop 0
	v_mfma_f32_32x32x16_bf16 v[2:17], v[76:79], v[80:83], v[2:17]
	ds_read_b64_tr_b16 v[76:77], v1 offset:2368
	ds_read_b64_tr_b16 v[78:79], v1 offset:2944
	ds_read_b128 v[80:83], v18 offset:46112
	s_waitcnt lgkmcnt(0)
	v_mfma_f32_32x32x16_bf16 v[2:17], v[76:79], v[80:83], v[2:17]
	s_nop 11
	v_cvt_pk_bf16_f32 v2, v2, v3
	v_cvt_pk_bf16_f32 v3, v4, v5
	v_cvt_pk_bf16_f32 v4, v6, v7
	v_cvt_pk_bf16_f32 v5, v8, v9
	ds_write2_b64 v84, v[2:3], v[4:5] offset0:128 offset1:130
	v_cvt_pk_bf16_f32 v2, v10, v11
	v_cvt_pk_bf16_f32 v3, v12, v13
	v_cvt_pk_bf16_f32 v4, v14, v15
	v_cvt_pk_bf16_f32 v5, v16, v17
	ds_write2_b64 v84, v[2:3], v[4:5] offset0:132 offset1:134

.Lstg_8:
	v_mov_b32_e32 v2, v180
	v_cndmask_b32_e64 v3, 0, 1, s[82:83]
	v_cmp_ne_u32_e64 s[38:39], 1, v3
	v_ashrrev_i32_e32 v1, 5, v2
	s_andn2_b64 vcc, exec, s[82:83]
	v_and_b32_e32 v18, 31, v2
	s_cbranch_vccnz .LBB0_140
	v_and_b32_e32 v3, 16, v2
	v_lshrrev_b32_e32 v4, 2, v2
	v_lshlrev_b32_e32 v2, 2, v2
	v_and_b32_e32 v4, 0xffffffb, v4
	v_and_or_b32 v2, v2, 12, v3
	v_mov_b32_e32 v6, s76
	v_lshlrev_b32_e32 v2, 1, v2
	v_mul_lo_u32 v3, v4, s64
	v_mad_u32_u24 v84, v18, s64, v6
	v_add3_u32 v19, s76, v2, v3
	v_lshl_add_u32 v80, v1, 4, v84
	ds_read_b64_tr_b16 v[2:3], v19 offset:46080
	ds_read_b64_tr_b16 v[4:5], v19 offset:46656
	ds_read_b128 v[6:9], v80 offset:41472
	s_waitcnt lgkmcnt(0)
	v_mfma_f32_32x32x16_bf16 v[2:17], v[2:5], v[6:9], 0
	ds_read_b64_tr_b16 v[76:77], v19 offset:48384
	ds_read_b64_tr_b16 v[78:79], v19 offset:48960
	ds_read_b128 v[80:83], v80 offset:41504
	v_lshl_add_u32 v19, v1, 3, v84
	v_add_u32_e32 v19, 0x9000, v19
	s_waitcnt lgkmcnt(0)
	v_mfma_f32_32x32x16_bf16 v[2:17], v[76:79], v[80:83], v[2:17]
	s_nop 11
	v_cvt_pk_bf16_f32 v2, v2, v3
	v_cvt_pk_bf16_f32 v3, v4, v5
	v_cvt_pk_bf16_f32 v4, v6, v7
	v_cvt_pk_bf16_f32 v5, v8, v9
	v_cvt_pk_bf16_f32 v6, v10, v11
	v_cvt_pk_bf16_f32 v7, v12, v13
	v_cvt_pk_bf16_f32 v8, v14, v15
	v_cvt_pk_bf16_f32 v9, v16, v17
	ds_write2_b64 v19, v[2:3], v[4:5] offset0:8 offset1:10
	ds_write2_b64 v19, v[6:7], v[8:9] offset0:12 offset1:14
	s_andn2_b64 vcc, exec, s[84:85]
	s_cbranch_vccz .LBB0_141

.Lstg_9:
	v_mov_b32_e32 v1, v180
	s_and_b64 vcc, exec, s[38:39]
	s_cbranch_vccnz .LBB0_130
	v_and_b32_e32 v6, 31, v1
	v_ashrrev_i32_e32 v18, 5, v1
	v_and_b32_e32 v2, 16, v1
	v_lshrrev_b32_e32 v3, 2, v1
	v_lshlrev_b32_e32 v1, 2, v1
	v_and_b32_e32 v3, 0xffffffb, v3
	v_and_or_b32 v1, v1, 12, v2
	v_mov_b32_e32 v7, s76
	v_lshlrev_b32_e32 v1, 1, v1
	v_mul_lo_u32 v2, v3, s64
	v_mad_u32_u24 v19, v6, s64, v7
	v_add3_u32 v1, s76, v1, v2
	v_lshl_add_u32 v80, v18, 4, v19
	ds_read_b64_tr_b16 v[2:3], v1 offset:36928
	ds_read_b64_tr_b16 v[4:5], v1 offset:37504
	ds_read_b128 v[6:9], v80 offset:50752
	s_waitcnt lgkmcnt(0)
	v_mfma_f32_32x32x16_bf16 v[2:17], v[2:5], v[6:9], 0
	ds_read_b64_tr_b16 v[76:77], v1 offset:39232
	ds_read_b64_tr_b16 v[78:79], v1 offset:39808
	ds_read_b128 v[80:83], v80 offset:50784
	v_lshl_add_u32 v1, v18, 3, v19
	v_add_u32_e32 v1, 0xc000, v1
	s_waitcnt lgkmcnt(0)
	v_mfma_f32_32x32x16_bf16 v[2:17], v[76:79], v[80:83], v[2:17]
	s_nop 11
	v_cvt_pk_bf16_f32 v2, v2, v3
	v_cvt_pk_bf16_f32 v3, v4, v5
	v_cvt_pk_bf16_f32 v4, v6, v7
	v_cvt_pk_bf16_f32 v5, v8, v9
	v_cvt_pk_bf16_f32 v6, v10, v11
	v_cvt_pk_bf16_f32 v7, v12, v13
	v_cvt_pk_bf16_f32 v8, v14, v15
	v_cvt_pk_bf16_f32 v9, v16, v17
	ds_write2_b64 v1, v[2:3], v[4:5] offset0:192 offset1:194
	ds_write2_b64 v1, v[6:7], v[8:9] offset0:196 offset1:198
.LBB0_130:
	v_mov_b32_e32 v1, v180
	v_mov_b32_e32 v80, s76
	v_add_u32_e32 v2, s42, v1
	v_lshlrev_b32_e32 v1, 4, v1
	v_bfe_u32 v2, v2, 2, 6
	v_and_b32_e32 v1, 48, v1
	v_mad_u32_u24 v81, v2, s64, v80
	v_lshlrev_b32_e32 v2, 2, v1
	v_readlane_b32 s38, v253, 63
	v_readlane_b32 s39, v254, 0
	s_waitcnt vmcnt(1)
	v_lshlrev_b32_e32 v18, 16, v68
	v_add_u32_e32 v6, s38, v2
	v_add_u32_e32 v14, s39, v2
	ds_read_b128 v[2:5], v6
	ds_read_b128 v[6:9], v6 offset:16
	ds_read_b128 v[10:13], v14
	ds_read_b128 v[14:17], v14 offset:16
	v_and_b32_e32 v19, 0xffff0000, v68
	v_lshlrev_b32_e32 v76, 16, v72
	v_and_b32_e32 v77, 0xffff0000, v72
	v_lshlrev_b32_e32 v78, 16, v52
	v_and_b32_e32 v79, 0xffff0000, v52
	v_pk_add_f32 v[76:77], v[76:77], v[18:19] neg_lo:[0,1] neg_hi:[0,1]
	v_lshlrev_b32_e32 v52, 16, v53
	s_waitcnt lgkmcnt(3)
	v_pk_fma_f32 v[2:3], v[76:77], v[2:3], v[18:19]
	v_pk_add_f32 v[18:19], v[78:79], v[18:19] neg_lo:[0,1] neg_hi:[0,1]
	v_and_b32_e32 v53, 0xffff0000, v53
	s_waitcnt lgkmcnt(1)
	v_pk_fma_f32 v[2:3], v[18:19], v[10:11], v[2:3]
	v_lshlrev_b32_e32 v10, 16, v69
	v_and_b32_e32 v11, 0xffff0000, v69
	v_lshlrev_b32_e32 v18, 16, v73
	v_and_b32_e32 v19, 0xffff0000, v73
	v_pk_add_f32 v[18:19], v[18:19], v[10:11] neg_lo:[0,1] neg_hi:[0,1]
	v_cvt_pk_f16_f32 v2, v2, v3
	v_pk_fma_f32 v[4:5], v[18:19], v[4:5], v[10:11]
	v_pk_add_f32 v[10:11], v[52:53], v[10:11] neg_lo:[0,1] neg_hi:[0,1]
	v_lshlrev_b32_e32 v18, 16, v54
	v_pk_fma_f32 v[4:5], v[10:11], v[12:13], v[4:5]
	v_lshlrev_b32_e32 v10, 16, v70
	v_and_b32_e32 v11, 0xffff0000, v70
	v_lshlrev_b32_e32 v12, 16, v74
	v_and_b32_e32 v13, 0xffff0000, v74
	v_and_b32_e32 v19, 0xffff0000, v54
	v_pk_add_f32 v[12:13], v[12:13], v[10:11] neg_lo:[0,1] neg_hi:[0,1]
	v_cvt_pk_f16_f32 v3, v4, v5
	v_pk_fma_f32 v[6:7], v[12:13], v[6:7], v[10:11]
	v_pk_add_f32 v[10:11], v[18:19], v[10:11] neg_lo:[0,1] neg_hi:[0,1]
	v_lshlrev_b32_e32 v12, 16, v75
	s_waitcnt lgkmcnt(0)
	v_pk_fma_f32 v[6:7], v[10:11], v[14:15], v[6:7]
	v_and_b32_e32 v13, 0xffff0000, v75
	v_lshlrev_b32_e32 v14, 16, v71
	v_and_b32_e32 v15, 0xffff0000, v71
	v_lshlrev_b32_e32 v10, 16, v55
	v_and_b32_e32 v11, 0xffff0000, v55
	v_pk_add_f32 v[12:13], v[12:13], v[14:15] neg_lo:[0,1] neg_hi:[0,1]
	v_pk_add_f32 v[10:11], v[10:11], v[14:15] neg_lo:[0,1] neg_hi:[0,1]
	v_pk_fma_f32 v[8:9], v[12:13], v[8:9], v[14:15]
	v_cvt_pk_f16_f32 v4, v6, v7
	v_pk_fma_f32 v[8:9], v[10:11], v[16:17], v[8:9]
	v_lshl_add_u32 v6, v1, 1, v81
	v_cvt_pk_f16_f32 v5, v8, v9
	v_or_b32_e32 v1, 8, v1
	ds_write_b128 v6, v[2:5] offset:9216
	v_lshlrev_b32_e32 v2, 2, v1
	v_add_u32_e32 v6, s38, v2
	v_add_u32_e32 v14, s39, v2
	ds_read_b128 v[2:5], v6
	ds_read_b128 v[6:9], v6 offset:16
	ds_read_b128 v[10:13], v14
	ds_read_b128 v[14:17], v14 offset:16
	s_waitcnt vmcnt(0)
	v_lshlrev_b32_e32 v18, 16, v56
	v_and_b32_e32 v19, 0xffff0000, v56
	v_lshlrev_b32_e32 v52, 16, v60
	v_and_b32_e32 v53, 0xffff0000, v60
	v_lshlrev_b32_e32 v54, 16, v64
	v_and_b32_e32 v55, 0xffff0000, v64
	v_pk_add_f32 v[52:53], v[52:53], v[18:19] neg_lo:[0,1] neg_hi:[0,1]
	v_lshl_add_u32 v1, v1, 1, v81
	s_waitcnt lgkmcnt(3)
	v_pk_fma_f32 v[2:3], v[52:53], v[2:3], v[18:19]
	v_pk_add_f32 v[18:19], v[54:55], v[18:19] neg_lo:[0,1] neg_hi:[0,1]
	v_lshlrev_b32_e32 v52, 16, v65
	s_waitcnt lgkmcnt(1)
	v_pk_fma_f32 v[2:3], v[18:19], v[10:11], v[2:3]
	v_lshlrev_b32_e32 v10, 16, v57
	v_and_b32_e32 v11, 0xffff0000, v57
	v_lshlrev_b32_e32 v18, 16, v61
	v_and_b32_e32 v19, 0xffff0000, v61
	v_and_b32_e32 v53, 0xffff0000, v65
	v_pk_add_f32 v[18:19], v[18:19], v[10:11] neg_lo:[0,1] neg_hi:[0,1]
	v_cvt_pk_f16_f32 v2, v2, v3
	v_pk_fma_f32 v[4:5], v[18:19], v[4:5], v[10:11]
	v_pk_add_f32 v[10:11], v[52:53], v[10:11] neg_lo:[0,1] neg_hi:[0,1]
	v_lshlrev_b32_e32 v18, 16, v66
	v_pk_fma_f32 v[4:5], v[10:11], v[12:13], v[4:5]
	v_lshlrev_b32_e32 v10, 16, v58
	v_and_b32_e32 v11, 0xffff0000, v58
	v_lshlrev_b32_e32 v12, 16, v62
	v_and_b32_e32 v13, 0xffff0000, v62
	v_and_b32_e32 v19, 0xffff0000, v66
	v_pk_add_f32 v[12:13], v[12:13], v[10:11] neg_lo:[0,1] neg_hi:[0,1]
	v_cvt_pk_f16_f32 v3, v4, v5
	v_pk_fma_f32 v[6:7], v[12:13], v[6:7], v[10:11]
	v_pk_add_f32 v[10:11], v[18:19], v[10:11] neg_lo:[0,1] neg_hi:[0,1]
	v_lshlrev_b32_e32 v12, 16, v63
	s_waitcnt lgkmcnt(0)
	v_pk_fma_f32 v[6:7], v[10:11], v[14:15], v[6:7]
	v_and_b32_e32 v13, 0xffff0000, v63
	v_lshlrev_b32_e32 v14, 16, v59
	v_and_b32_e32 v15, 0xffff0000, v59
	v_lshlrev_b32_e32 v10, 16, v67
	v_and_b32_e32 v11, 0xffff0000, v67
	v_pk_add_f32 v[12:13], v[12:13], v[14:15] neg_lo:[0,1] neg_hi:[0,1]
	v_pk_add_f32 v[10:11], v[10:11], v[14:15] neg_lo:[0,1] neg_hi:[0,1]
	v_pk_fma_f32 v[8:9], v[12:13], v[8:9], v[14:15]
	v_cvt_pk_f16_f32 v4, v6, v7
	v_pk_fma_f32 v[8:9], v[10:11], v[16:17], v[8:9]
	s_nop 0
	v_cvt_pk_f16_f32 v5, v8, v9
	ds_write_b128 v1, v[2:5] offset:9216
	v_mov_b32_e32 v1, v180
	s_waitcnt lgkmcnt(0)
	s_barrier
	s_bitcmp1_b32 s60, 0
	s_cbranch_scc1 .Lstg_10
	s_sleep 4
.Lstg_10:
	s_nop 0
	v_and_or_b32 v2, v1, 31, s43
	v_ashrrev_i32_e32 v18, 5, v1
	v_mad_u32_u24 v19, v2, s64, v80
	v_lshl_add_u32 v6, v18, 4, v19
	ds_read_b128 v[2:5], v6 offset:46080
	ds_read_b128 v[68:71], v6 offset:46112
	ds_read_b128 v[72:75], v6 offset:46144
	ds_read_b128 v[76:79], v6 offset:46176
	v_and_b32_e32 v6, 16, v1
	v_lshrrev_b32_e32 v7, 2, v1
	v_lshlrev_b32_e32 v1, 2, v1
	v_and_b32_e32 v1, 12, v1
	v_and_b32_e32 v7, 0xffffffb, v7
	v_or3_b32 v1, v6, v1, s91
	v_lshlrev_b32_e32 v1, 1, v1
	v_mul_lo_u32 v6, v7, s64
	v_add3_u32 v1, s76, v1, v6
	ds_read_b64_tr_b16 v[6:7], v1
	ds_read_b64_tr_b16 v[8:9], v1 offset:576
	ds_read_b64_tr_b16 v[80:81], v1 offset:2304
	ds_read_b64_tr_b16 v[82:83], v1 offset:2880
	ds_read_b64_tr_b16 v[84:85], v1 offset:4608
	ds_read_b64_tr_b16 v[86:87], v1 offset:5184
	ds_read_b64_tr_b16 v[88:89], v1 offset:6912
	ds_read_b64_tr_b16 v[90:91], v1 offset:7488
	ds_read_b64_tr_b16 v[10:11], v1 offset:55296
	ds_read_b64_tr_b16 v[12:13], v1 offset:55872
	ds_read_b64_tr_b16 v[92:93], v1 offset:57600
	ds_read_b64_tr_b16 v[94:95], v1 offset:58176
	ds_read_b64_tr_b16 v[96:97], v1 offset:59904
	ds_read_b64_tr_b16 v[98:99], v1 offset:60480
	ds_read_b64_tr_b16 v[182:183], v1 offset:62208
	ds_read_b64_tr_b16 v[184:185], v1 offset:62784
	s_waitcnt lgkmcnt(14)
	v_mfma_f32_32x32x16_bf16 v[52:67], v[6:9], v[2:5], 0
	v_lshlrev_b32_e32 v1, 3, v18
	v_add3_u32 v1, v19, v1, s28
	s_xor_b32 s40, s50, 63
	s_and_b64 s[38:39], s[36:37], exec
	s_cselect_b32 s38, s50, s40
	s_lshl_b32 s39, s68, 10
	s_add_i32 s39, s24, s39
	s_waitcnt lgkmcnt(6)
	v_mfma_f32_32x32x16_bf16 v[2:17], v[10:13], v[2:5], 0
	s_or_b32 s56, s39, s38
	s_cmpk_gt_i32 s56, 0x7ff
	s_mov_b64 vcc, -1
	v_mfma_f32_32x32x16_bf16 v[52:67], v[80:83], v[68:71], v[52:67]
	s_waitcnt lgkmcnt(4)
	v_mfma_f32_32x32x16_bf16 v[2:17], v[92:95], v[68:71], v[2:17]
	v_mfma_f32_32x32x16_bf16 v[52:67], v[84:87], v[72:75], v[52:67]
	s_waitcnt lgkmcnt(2)
	v_mfma_f32_32x32x16_bf16 v[2:17], v[96:99], v[72:75], v[2:17]
	v_mfma_f32_32x32x16_bf16 v[52:67], v[88:91], v[76:79], v[52:67]
	s_waitcnt lgkmcnt(0)
	v_mfma_f32_32x32x16_bf16 v[2:17], v[182:185], v[76:79], v[2:17]
	s_nop 9
	v_cvt_pk_bf16_f32 v18, v52, v53
	v_cvt_pk_bf16_f32 v19, v54, v55
	v_cvt_pk_bf16_f32 v52, v56, v57
	v_cvt_pk_bf16_f32 v53, v58, v59
	v_add_u32_e32 v54, 0x9000, v1
	v_add_u32_e32 v1, 0x6800, v1
	ds_write2_b64 v54, v[18:19], v[52:53] offset1:2
	v_cvt_pk_bf16_f32 v2, v2, v3
	v_cvt_pk_bf16_f32 v3, v4, v5
	v_cvt_pk_bf16_f32 v4, v6, v7
	v_cvt_pk_bf16_f32 v5, v8, v9
	v_cvt_pk_bf16_f32 v18, v60, v61
	v_cvt_pk_bf16_f32 v19, v62, v63
	v_cvt_pk_bf16_f32 v52, v64, v65
	v_cvt_pk_bf16_f32 v53, v66, v67
	ds_write2_b64 v1, v[2:3], v[4:5] offset0:128 offset1:130
	v_cvt_pk_bf16_f32 v2, v10, v11
	v_cvt_pk_bf16_f32 v3, v12, v13
	v_cvt_pk_bf16_f32 v4, v14, v15
	v_cvt_pk_bf16_f32 v5, v16, v17
	ds_write2_b64 v54, v[18:19], v[52:53] offset0:4 offset1:6
	ds_write2_b64 v1, v[2:3], v[4:5] offset0:132 offset1:134
	s_waitcnt lgkmcnt(0)
	s_barrier
	s_cbranch_scc0 .LBB0_132
	v_readlane_b32 s38, v254, 59
	v_readlane_b32 s39, v254, 60
	s_load_dwordx2 s[38:39], s[38:39], 0xa8
	s_add_i32 s50, s56, 0xfffff800
	s_mov_b64 vcc, 0
	s_mov_b64 s[68:69], s[50:51]

.LBB0_134:
	s_bitcmp1_b32 s60, 0
	s_cbranch_scc1 .Lstg_11
	s_sleep 4
.Lstg_11:
	v_mov_b32_e32 v19, v180
	s_lshl_b64 s[40:41], s[68:69], 15
	v_and_b32_e32 v181, 31, v19
	v_ashrrev_i32_e32 v1, 5, v19
	v_or_b32_e32 v18, s43, v181
	v_mul_u32_u24_e32 v2, 0x90, v18
	v_lshlrev_b32_e32 v3, 4, v1
	v_add3_u32 v212, s29, v2, v3
	v_and_b32_e32 v2, 16, v19
	v_lshlrev_b32_e32 v4, 2, v19
	v_lshrrev_b32_e32 v3, 2, v19
	v_and_or_b32 v2, v4, 12, v2
	v_and_b32_e32 v3, 0xffffffb, v3
	v_or_b32_e32 v4, s91, v2
	v_lshlrev_b32_e32 v4, 1, v4
	v_mul_lo_u32 v3, v3, s64
	v_or_b32_e32 v2, s43, v2
	v_add3_u32 v213, s76, v4, v3
	v_add_u32_e32 v3, s76, v3
	v_add_u32_e32 v214, v3, v4
	v_lshl_add_u32 v238, v2, 1, v3
	ds_read_b128 v[2:5], v212
	ds_read_b128 v[182:185], v212 offset:32
	ds_read_b64_tr_b16 v[6:7], v213 offset:36864
	ds_read_b64_tr_b16 v[8:9], v213 offset:37440
	ds_read_b64_tr_b16 v[186:187], v213 offset:39168
	ds_read_b64_tr_b16 v[188:189], v213 offset:39744
	ds_read_b64_tr_b16 v[10:11], v214 offset:18432
	ds_read_b64_tr_b16 v[12:13], v214 offset:19008
	ds_read_b64_tr_b16 v[190:191], v214 offset:20736
	ds_read_b64_tr_b16 v[192:193], v214 offset:21312
	ds_read_b64_tr_b16 v[14:15], v214 offset:27648
	ds_read_b64_tr_b16 v[16:17], v214 offset:28224
	ds_read_b64_tr_b16 v[196:197], v214 offset:29952
	ds_read_b64_tr_b16 v[198:199], v214 offset:30528
	ds_read_b64_tr_b16 v[52:53], v238 offset:18432
	ds_read_b64_tr_b16 v[54:55], v238 offset:19008
	ds_read_b64_tr_b16 v[200:201], v238 offset:20736
	ds_read_b64_tr_b16 v[202:203], v238 offset:21312
	ds_read_b64_tr_b16 v[204:205], v238 offset:27648
	ds_read_b64_tr_b16 v[206:207], v238 offset:28224
	ds_read_b64_tr_b16 v[208:209], v238 offset:29952
	ds_read_b64_tr_b16 v[210:211], v238 offset:30528
	s_waitcnt lgkmcnt(0)
	s_add_u32 s38, s38, s40
	s_addc_u32 s39, s39, s41
	v_mfma_f32_32x32x16_bf16 v[68:83], v[6:9], v[2:5], 0
	v_mfma_f32_32x32x16_bf16 v[84:99], v[14:17], v[2:5], 0
	v_mfma_f32_32x32x16_bf16 v[52:67], v[6:9], v[52:55], 0
	v_mfma_f32_32x32x16_bf16 v[2:17], v[10:13], v[204:207], 0
	v_mfma_f32_32x32x16_bf16 v[2:17], v[190:193], v[208:211], v[2:17]
	v_mfma_f32_32x32x16_bf16 v[68:83], v[186:189], v[182:185], v[68:83]
	v_mfma_f32_32x32x16_bf16 v[84:99], v[196:199], v[182:185], v[84:99]
	v_mfma_f32_32x32x16_bf16 v[52:67], v[186:189], v[200:203], v[52:67]
	ds_read_b128 v[182:185], v212 offset:64
	ds_read_b128 v[186:189], v212 offset:96
	ds_read_b64_tr_b16 v[190:191], v213 offset:41472
	ds_read_b64_tr_b16 v[192:193], v213 offset:42048
	ds_read_b64_tr_b16 v[196:197], v213 offset:43776
	ds_read_b64_tr_b16 v[198:199], v213 offset:44352
	ds_read_b64_tr_b16 v[202:203], v214 offset:23616
	ds_read_b64_tr_b16 v[204:205], v214 offset:32256
	ds_read_b64_tr_b16 v[208:209], v214 offset:25344
	ds_read_b64_tr_b16 v[210:211], v214 offset:25920
	ds_read_b64_tr_b16 v[200:201], v214 offset:23040
	ds_read_b64_tr_b16 v[206:207], v214 offset:32832
	ds_read_b64_tr_b16 v[212:213], v214 offset:34560
	ds_read_b64_tr_b16 v[214:215], v214 offset:35136
	ds_read_b64_tr_b16 v[218:219], v238 offset:23616
	ds_read_b64_tr_b16 v[228:229], v238 offset:32256
	ds_read_b64_tr_b16 v[232:233], v238 offset:25344
	ds_read_b64_tr_b16 v[234:235], v238 offset:25920
	ds_read_b64_tr_b16 v[216:217], v238 offset:23040
	ds_read_b64_tr_b16 v[230:231], v238 offset:32832
	ds_read_b64_tr_b16 v[236:237], v238 offset:34560
	ds_read_b64_tr_b16 v[238:239], v238 offset:35136
	s_waitcnt lgkmcnt(2)
	v_mfma_f32_32x32x16_bf16 v[2:17], v[200:203], v[228:231], v[2:17]
	v_mfma_f32_32x32x16_bf16 v[68:83], v[190:193], v[182:185], v[68:83]
	v_mfma_f32_32x32x16_bf16 v[84:99], v[204:207], v[182:185], v[84:99]
	v_mfma_f32_32x32x16_bf16 v[52:67], v[190:193], v[216:219], v[52:67]
	s_waitcnt lgkmcnt(0)
	v_mfma_f32_32x32x16_bf16 v[2:17], v[208:211], v[236:239], v[2:17]
	v_mfma_f32_32x32x16_bf16 v[68:83], v[196:199], v[186:189], v[68:83]
	v_mfma_f32_32x32x16_bf16 v[84:99], v[212:215], v[186:189], v[84:99]
	v_mfma_f32_32x32x16_bf16 v[52:67], v[196:199], v[232:235], v[52:67]
	v_lshl_add_u32 v190, v1, 2, s91
	v_cmp_eq_u32_e32 vcc, v190, v18
	v_or_b32_e32 v200, 1, v190
	v_or_b32_e32 v192, 3, v190
	v_cndmask_b32_e64 v183, 0, 1.0, vcc
	v_cmp_eq_u32_e32 vcc, v200, v18
	v_or_b32_e32 v193, 2, v190
	v_add_u32_e32 v196, 9, v190
	v_add_u32_e32 v197, 8, v190
	v_add_u32_e32 v198, 11, v190
	v_add_u32_e32 v199, 10, v190
	v_sub_f32_e32 v84, v36, v84
	v_cndmask_b32_e64 v36, 0, 1.0, vcc
	v_lshl_add_u32 v182, v18, 2, s87
	v_sub_f32_e32 v191, v183, v52
	v_lshl_add_u32 v183, v190, 2, s87
	v_lshl_add_u32 v184, v193, 2, s87
	v_lshl_add_u32 v185, v192, 2, s87
	v_lshl_add_u32 v186, v197, 2, s87
	v_lshl_add_u32 v187, v196, 2, s87
	v_lshl_add_u32 v188, v199, 2, s87
	v_lshl_add_u32 v189, v198, 2, s87
	v_sub_f32_e32 v36, v36, v53
	v_pk_add_f32 v[2:3], v[152:153], v[2:3] neg_lo:[0,1] neg_hi:[0,1]
	v_cmp_eq_u32_e32 vcc, v192, v18
	ds_read_b32 v52, v182
	ds_read_b64 v[182:183], v183
	ds_read_b32 v184, v184
	ds_read_b32 v185, v185
	ds_read_b32 v186, v186
	ds_read_b32 v187, v187
	ds_read_b32 v188, v188
	ds_read_b32 v189, v189
	v_pk_add_f32 v[68:69], v[154:155], v[68:69] neg_lo:[0,1] neg_hi:[0,1]
	v_sub_f32_e32 v85, v37, v85
	s_waitcnt lgkmcnt(7)
	v_mul_f32_e32 v154, v36, v52
	s_waitcnt lgkmcnt(6)
	v_pk_mul_f32 v[36:37], v[2:3], v[182:183]
	v_cndmask_b32_e64 v3, 0, 1.0, vcc
	v_cmp_eq_u32_e32 vcc, v193, v18
	v_sub_f32_e32 v89, v41, v89
	v_sub_f32_e32 v88, v40, v88
	v_cndmask_b32_e64 v2, 0, 1.0, vcc
	v_pk_add_f32 v[2:3], v[2:3], v[54:55] neg_lo:[0,1] neg_hi:[0,1]
	v_cmp_eq_u32_e32 vcc, v196, v18
	v_pk_mul_f32 v[40:41], v[2:3], v[52:53] op_sel_hi:[1,0]
	v_pk_add_f32 v[2:3], v[150:151], v[4:5] neg_lo:[0,1] neg_hi:[0,1]
	v_sub_f32_e32 v91, v43, v91
	v_sub_f32_e32 v90, v42, v90
	s_waitcnt lgkmcnt(4)
	v_pk_mul_f32 v[42:43], v[2:3], v[184:185]
	v_cndmask_b32_e64 v3, 0, 1.0, vcc
	v_cmp_eq_u32_e32 vcc, v197, v18
	v_sub_f32_e32 v97, v49, v97
	v_sub_f32_e32 v96, v48, v96
	v_cndmask_b32_e64 v2, 0, 1.0, vcc
	v_pk_add_f32 v[2:3], v[2:3], v[56:57] neg_lo:[0,1] neg_hi:[0,1]
	v_cmp_eq_u32_e32 vcc, v198, v18
	v_pk_mul_f32 v[4:5], v[2:3], v[52:53] op_sel_hi:[1,0]
	v_pk_add_f32 v[2:3], v[166:167], v[6:7] neg_lo:[0,1] neg_hi:[0,1]
	v_sub_f32_e32 v93, v45, v93
	s_waitcnt lgkmcnt(2)
	v_pk_mul_f32 v[6:7], v[2:3], v[186:187]
	v_cndmask_b32_e64 v3, 0, 1.0, vcc
	v_cmp_eq_u32_e32 vcc, v199, v18
	v_sub_f32_e32 v92, v44, v92
	v_pk_add_f32 v[44:45], v[164:165], v[72:73] neg_lo:[0,1] neg_hi:[0,1]
	v_cndmask_b32_e64 v2, 0, 1.0, vcc
	v_pk_add_f32 v[2:3], v[2:3], v[58:59] neg_lo:[0,1] neg_hi:[0,1]
	v_add_u32_e32 v72, 26, v190
	v_pk_mul_f32 v[48:49], v[2:3], v[52:53] op_sel_hi:[1,0]
	v_pk_add_f32 v[2:3], v[156:157], v[8:9] neg_lo:[0,1] neg_hi:[0,1]
	v_add_u32_e32 v53, 16, v190
	s_waitcnt lgkmcnt(0)
	v_pk_mul_f32 v[8:9], v[2:3], v[188:189]
	v_add_u32_e32 v2, 17, v190
	v_cmp_eq_u32_e32 vcc, v2, v18
	v_lshl_add_u32 v56, v53, 2, s87
	v_mul_f32_e32 v191, v191, v52
	v_cndmask_b32_e64 v3, 0, 1.0, vcc
	v_cmp_eq_u32_e32 vcc, v53, v18
	v_cvt_pk_f16_f32 v4, v4, v5
	v_cvt_pk_f16_f32 v5, v48, v49
	v_cndmask_b32_e64 v2, 0, 1.0, vcc
	v_pk_add_f32 v[2:3], v[2:3], v[60:61] neg_lo:[0,1] neg_hi:[0,1]
	v_add_u32_e32 v61, 24, v190
	v_pk_mul_f32 v[54:55], v[2:3], v[52:53] op_sel_hi:[1,0]
	v_pk_add_f32 v[2:3], v[170:171], v[10:11] neg_lo:[0,1] neg_hi:[0,1]
	ds_read_b64 v[10:11], v56
	v_add_u32_e32 v53, 18, v190
	v_lshl_add_u32 v56, v53, 2, s87
	v_lshl_add_u32 v58, v61, 2, s87
	v_lshl_add_u32 v60, v72, 2, s87
	s_waitcnt lgkmcnt(0)
	v_pk_mul_f32 v[10:11], v[2:3], v[10:11]
	v_add_u32_e32 v2, 19, v190
	v_cmp_eq_u32_e32 vcc, v2, v18
	ds_read_b64 v[56:57], v56
	ds_read_b64 v[58:59], v58
	ds_read_b32 v60, v60
	v_cndmask_b32_e64 v3, 0, 1.0, vcc
	v_cmp_eq_u32_e32 vcc, v53, v18
	v_sub_f32_e32 v87, v39, v87
	v_sub_f32_e32 v86, v38, v86
	v_cndmask_b32_e64 v2, 0, 1.0, vcc
	v_pk_add_f32 v[2:3], v[2:3], v[62:63] neg_lo:[0,1] neg_hi:[0,1]
	v_pk_add_f32 v[38:39], v[148:149], v[70:71] neg_lo:[0,1] neg_hi:[0,1]
	v_pk_mul_f32 v[62:63], v[2:3], v[52:53] op_sel_hi:[1,0]
	v_pk_add_f32 v[2:3], v[162:163], v[12:13] neg_lo:[0,1] neg_hi:[0,1]
	s_add_u32 s40, s38, 0x2000
	s_waitcnt lgkmcnt(2)
	v_pk_mul_f32 v[12:13], v[2:3], v[56:57]
	v_add_u32_e32 v2, 25, v190
	v_cmp_eq_u32_e32 vcc, v2, v18
	v_sub_f32_e32 v95, v47, v95
	v_sub_f32_e32 v94, v46, v94
	v_cndmask_b32_e64 v3, 0, 1.0, vcc
	v_cmp_eq_u32_e32 vcc, v61, v18
	v_pk_add_f32 v[46:47], v[158:159], v[74:75] neg_lo:[0,1] neg_hi:[0,1]
	s_addc_u32 s41, s39, 0
	v_cndmask_b32_e64 v2, 0, 1.0, vcc
	v_pk_add_f32 v[2:3], v[2:3], v[64:65] neg_lo:[0,1] neg_hi:[0,1]
	v_sub_f32_e32 v99, v51, v99
	v_pk_mul_f32 v[64:65], v[2:3], v[52:53] op_sel_hi:[1,0]
	v_pk_add_f32 v[2:3], v[178:179], v[14:15] neg_lo:[0,1] neg_hi:[0,1]
	v_sub_f32_e32 v98, v50, v98
	s_waitcnt lgkmcnt(1)
	v_pk_mul_f32 v[14:15], v[2:3], v[58:59]
	v_add_u32_e32 v2, 27, v190
	v_cmp_eq_u32_e32 vcc, v2, v18
	v_lshl_add_u32 v2, v2, 2, s87
	ds_read_b32 v61, v2
	v_cndmask_b32_e64 v3, 0, 1.0, vcc
	v_cmp_eq_u32_e32 vcc, v72, v18
	v_pk_add_f32 v[50:51], v[174:175], v[76:77] neg_lo:[0,1] neg_hi:[0,1]
	v_pk_add_f32 v[70:71], v[160:161], v[78:79] neg_lo:[0,1] neg_hi:[0,1]
	v_cndmask_b32_e64 v2, 0, 1.0, vcc
	v_pk_add_f32 v[2:3], v[2:3], v[66:67] neg_lo:[0,1] neg_hi:[0,1]
	v_pk_add_f32 v[56:57], v[176:177], v[80:81] neg_lo:[0,1] neg_hi:[0,1]
	v_pk_mul_f32 v[52:53], v[2:3], v[52:53] op_sel_hi:[1,0]
	v_pk_add_f32 v[2:3], v[168:169], v[16:17] neg_lo:[0,1] neg_hi:[0,1]
	v_pk_add_f32 v[58:59], v[172:173], v[82:83] neg_lo:[0,1] neg_hi:[0,1]
	s_waitcnt lgkmcnt(0)
	v_pk_mul_f32 v[16:17], v[2:3], v[60:61]
	v_lshlrev_b32_e32 v60, 3, v19
	v_bitop3_b32 v2, v181, 63, s43 bitop3:0x36
	v_cvt_pk_f16_f32 v3, v40, v41
	v_add_u32_e32 v40, s66, v60
	v_cndmask_b32_e64 v2, v2, v18, s[36:37]
	v_ashrrev_i32_e32 v41, 31, v40
	v_lshlrev_b32_e32 v61, 1, v2
	v_bfi_b32 v19, 31, v2, v19
	v_cvt_pk_f16_f32 v2, v191, v154
	v_lshl_add_u64 v[40:41], v[40:41], 1, s[38:39]
	global_store_dwordx4 v[40:41], v[2:5], off nt
	v_and_or_b32 v40, v61, 64, s3
	v_lshlrev_b32_e32 v1, 3, v1
	v_cvt_pk_f16_f32 v3, v38, v39
	v_add_lshl_u32 v38, v40, v19, 3
	v_ashrrev_i32_e32 v39, 31, v38
	v_cvt_pk_f16_f32 v2, v68, v69
	v_cvt_pk_f16_f32 v4, v44, v45
	v_cvt_pk_f16_f32 v5, v46, v47
	v_lshl_add_u64 v[38:39], v[38:39], 1, s[40:41]
	global_store_dwordx4 v[38:39], v[2:5], off nt
	v_add_u32_e32 v38, s25, v60
	v_ashrrev_i32_e32 v39, 31, v38
	v_cvt_pk_f16_f32 v2, v54, v55
	v_cvt_pk_f16_f32 v3, v62, v63
	v_cvt_pk_f16_f32 v4, v64, v65
	v_cvt_pk_f16_f32 v5, v52, v53
	v_lshl_add_u64 v[38:39], v[38:39], 1, s[38:39]
	global_store_dwordx4 v[38:39], v[2:5], off nt
	v_or_b32_e32 v38, 0x80, v40
	v_add_lshl_u32 v38, v38, v19, 3
	v_ashrrev_i32_e32 v39, 31, v38
	v_cvt_pk_f16_f32 v2, v50, v51
	v_cvt_pk_f16_f32 v3, v70, v71
	v_cvt_pk_f16_f32 v4, v56, v57
	v_cvt_pk_f16_f32 v5, v58, v59
	v_lshl_add_u64 v[38:39], v[38:39], 1, s[40:41]
	global_store_dwordx4 v[38:39], v[2:5], off nt
	s_nop 1
	v_mov_b32_e32 v2, s76
	v_mad_u32_u24 v2, v18, s64, v2
	v_add3_u32 v1, v2, v1, s28
	v_cvt_pk_f16_f32 v2, v84, v85
	v_cvt_pk_f16_f32 v3, v86, v87
	v_cvt_pk_f16_f32 v4, v88, v89
	v_cvt_pk_f16_f32 v5, v90, v91
	ds_write2_b64 v1, v[2:3], v[4:5] offset1:2
	v_cvt_pk_f16_f32 v2, v92, v93
	v_cvt_pk_f16_f32 v3, v94, v95
	v_cvt_pk_f16_f32 v4, v96, v97
	v_cvt_pk_f16_f32 v5, v98, v99
	ds_write2_b64 v1, v[2:3], v[4:5] offset0:4 offset1:6
	v_cvt_pk_f16_f32 v2, v36, v37
	v_cvt_pk_f16_f32 v3, v42, v43
	v_cvt_pk_f16_f32 v4, v6, v7
	v_cvt_pk_f16_f32 v5, v8, v9
	v_add_u32_e32 v1, 0xd800, v1
	ds_write2_b64 v1, v[2:3], v[4:5] offset1:2
	v_cvt_pk_f16_f32 v2, v10, v11
	v_cvt_pk_f16_f32 v3, v12, v13
	v_cvt_pk_f16_f32 v4, v14, v15
	v_cvt_pk_f16_f32 v5, v16, v17
	ds_write2_b64 v1, v[2:3], v[4:5] offset0:4 offset1:6
	v_mov_b32_e32 v18, v180
	s_waitcnt lgkmcnt(0)
	s_barrier
	s_bitcmp1_b32 s60, 0
	s_cbranch_scc1 .Lstg_12
	s_sleep 4
.Lstg_12:
	s_nop 0
	v_and_b32_e32 v2, 16, v18
	v_lshlrev_b32_e32 v4, 2, v18
	v_lshrrev_b32_e32 v3, 2, v18
	v_and_or_b32 v19, v4, 12, v2
	v_and_b32_e32 v3, 0xffffffb, v3
	v_or_b32_e32 v2, s43, v19
	v_or_b32_e32 v19, s91, v19
	v_lshlrev_b32_e32 v2, 1, v2
	v_mul_lo_u32 v36, v3, s64
	v_lshlrev_b32_e32 v19, 1, v19
	v_add3_u32 v16, s76, v2, v36
	v_add3_u32 v19, s76, v19, v36
	ds_read_b64_tr_b16 v[2:3], v16 offset:9216
	ds_read_b64_tr_b16 v[4:5], v16 offset:9792
	ds_read_b64_tr_b16 v[6:7], v16 offset:11520
	ds_read_b64_tr_b16 v[8:9], v16 offset:12096
	ds_read_b64_tr_b16 v[10:11], v16 offset:13824
	ds_read_b64_tr_b16 v[12:13], v16 offset:14400
	ds_read_b64_tr_b16 v[14:15], v16 offset:16128
	ds_read_b64_tr_b16 v[16:17], v16 offset:16704
	ds_read_b64_tr_b16 v[36:37], v19 offset:55296
	ds_read_b64_tr_b16 v[38:39], v19 offset:55872
	ds_read_b64_tr_b16 v[52:53], v19 offset:57600
	ds_read_b64_tr_b16 v[54:55], v19 offset:58176
	ds_read_b64_tr_b16 v[56:57], v19 offset:59904
	ds_read_b64_tr_b16 v[58:59], v19 offset:60480
	ds_read_b64_tr_b16 v[60:61], v19 offset:62208
	ds_read_b64_tr_b16 v[62:63], v19 offset:62784
	ds_read_b64_tr_b16 v[64:65], v19 offset:9216
	ds_read_b64_tr_b16 v[66:67], v19 offset:9792
	ds_read_b64_tr_b16 v[68:69], v19 offset:11520
	ds_read_b64_tr_b16 v[70:71], v19 offset:12096
	ds_read_b64_tr_b16 v[72:73], v19 offset:13824
	ds_read_b64_tr_b16 v[74:75], v19 offset:14400
	ds_read_b64_tr_b16 v[76:77], v19 offset:16128
	ds_read_b64_tr_b16 v[78:79], v19 offset:16704
	v_ashrrev_i32_e32 v1, 5, v18
	v_and_or_b32 v18, v18, 31, s43
	v_mul_u32_u24_e32 v19, 0x90, v18
	v_lshlrev_b32_e32 v96, 4, v1
	v_add3_u32 v19, s76, v19, v96
	ds_read_b128 v[80:83], v19
	ds_read_b128 v[84:87], v19 offset:32
	ds_read_b128 v[88:91], v19 offset:64
	ds_read_b128 v[92:95], v19 offset:96
	s_waitcnt lgkmcnt(14)
	v_mfma_f32_32x32x16_f16 v[36:51], v[36:39], v[2:5], 0
	v_mfma_f32_32x32x16_f16 v[36:51], v[52:55], v[6:9], v[36:51]
	v_mfma_f32_32x32x16_f16 v[36:51], v[56:59], v[10:13], v[36:51]
	s_waitcnt lgkmcnt(12)
	v_mfma_f32_32x32x16_f16 v[36:51], v[60:63], v[14:17], v[36:51]
	s_waitcnt lgkmcnt(3)
	v_mfma_f32_32x32x16_f16 v[2:17], v[64:67], v[80:83], 0
	s_nop 9
	v_cvt_pk_f16_f32 v36, v36, v37
	v_cvt_pk_f16_f32 v37, v38, v39
	v_cvt_pk_f16_f32 v38, v40, v41
	v_or_b32_e32 v40, s28, v18
	v_lshl_add_u32 v18, v40, 5, v96
	v_ashrrev_i32_e32 v19, 31, v18
	v_lshl_add_u64 v[18:19], v[18:19], 1, s[38:39]
	s_waitcnt lgkmcnt(2)
	v_mfma_f32_32x32x16_f16 v[2:17], v[68:71], v[84:87], v[2:17]
	s_mov_b64 s[38:39], 0x4000
	v_cvt_pk_f16_f32 v39, v42, v43
	v_cvt_pk_f16_f32 v43, v46, v47
	v_lshl_add_u64 v[46:47], v[18:19], 0, s[38:39]
	s_movk_i32 s38, 0x4000
	v_cvt_pk_f16_f32 v42, v44, v45
	v_cvt_pk_f16_f32 v44, v48, v49
	s_waitcnt lgkmcnt(1)
	v_mfma_f32_32x32x16_f16 v[2:17], v[72:75], v[88:91], v[2:17]
	v_add_co_u32_e32 v48, vcc, s38, v18
	v_cvt_pk_f16_f32 v45, v50, v51
	s_nop 0
	v_addc_co_u32_e32 v49, vcc, 0, v19, vcc
	global_store_dwordx4 v[48:49], v[36:39], off nt
	global_store_dwordx4 v[46:47], v[42:45], off offset:16 nt
	s_andn2_b64 vcc, exec, s[60:61]
	s_waitcnt lgkmcnt(0)
	v_mfma_f32_32x32x16_f16 v[2:17], v[76:79], v[92:95], v[2:17]
	s_mov_b64 s[38:39], -1
	s_nop 10
	v_cvt_pk_f16_f32 v36, v2, v3
	v_cvt_pk_f16_f32 v37, v4, v5
	v_cvt_pk_f16_f32 v38, v6, v7
	v_cvt_pk_f16_f32 v39, v8, v9
	v_cvt_pk_f16_f32 v2, v10, v11
	v_cvt_pk_f16_f32 v3, v12, v13
	v_cvt_pk_f16_f32 v4, v14, v15
	v_cvt_pk_f16_f32 v5, v16, v17
	s_cbranch_vccnz .LBB0_136
	v_lshlrev_b32_e32 v6, 1, v40
	s_movk_i32 s38, 0x7e
	v_xad_u32 v1, v6, s38, v1
	v_lshl_add_u32 v1, v1, 5, 0
	v_add_u32_e32 v1, 0x14400, v1
	s_mov_b64 s[38:39], 0
	ds_write_b128 v1, v[36:39]
	ds_write_b128 v1, v[2:5] offset:16
